# P0: w_in transpose loads batched (32 in flight), adaLN GEMV hand-pipelined; XCD-hierarchical seams; G2 l0 epilogue pipelined
# speedup vs baseline: 1.0489x; 1.0223x over previous
; __device__ __forceinline__ float siluf_(float x) { return x * sigmoidf_(x); }
; __device__ __forceinline__ void p0_phase(LAS unsigned char* lds, const float* c, const float* w_ada, const float* b_ada, const float* w_in, const float* w_out,
;                                          float* mod, bf16* win_t, bf16* wout_t, int tid, int wid, int lane) {
;     ...
;         for (int i = tid; i < 32 * 1024; i += 512) { const float cv = c[i]; cs[i] = siluf_(cv); }
.LBB0_19:
	global_load_dword v16, v[0:1], off
	v_lshl_add_u64 v[0:1], v[0:1], 0, s[12:13]
	global_load_dword v17, v[0:1], off
	v_lshl_add_u64 v[0:1], v[0:1], 0, s[12:13]
	global_load_dword v18, v[0:1], off
	v_lshl_add_u64 v[0:1], v[0:1], 0, s[12:13]
	global_load_dword v19, v[0:1], off
	v_lshl_add_u64 v[0:1], v[0:1], 0, s[12:13]
	global_load_dword v20, v[0:1], off
	v_lshl_add_u64 v[0:1], v[0:1], 0, s[12:13]
	global_load_dword v21, v[0:1], off
	v_lshl_add_u64 v[0:1], v[0:1], 0, s[12:13]
	global_load_dword v22, v[0:1], off
	v_lshl_add_u64 v[0:1], v[0:1], 0, s[12:13]
	global_load_dword v23, v[0:1], off
	v_lshl_add_u64 v[0:1], v[0:1], 0, s[12:13]
	global_load_dword v24, v[0:1], off
	v_lshl_add_u64 v[0:1], v[0:1], 0, s[12:13]
	global_load_dword v25, v[0:1], off
	v_lshl_add_u64 v[0:1], v[0:1], 0, s[12:13]
	global_load_dword v26, v[0:1], off
	v_lshl_add_u64 v[0:1], v[0:1], 0, s[12:13]
	global_load_dword v27, v[0:1], off
	v_lshl_add_u64 v[0:1], v[0:1], 0, s[12:13]
	global_load_dword v28, v[0:1], off
	v_lshl_add_u64 v[0:1], v[0:1], 0, s[12:13]
	global_load_dword v29, v[0:1], off
	v_lshl_add_u64 v[0:1], v[0:1], 0, s[12:13]
	global_load_dword v30, v[0:1], off
	v_lshl_add_u64 v[0:1], v[0:1], 0, s[12:13]
	global_load_dword v31, v[0:1], off
	v_lshl_add_u64 v[0:1], v[0:1], 0, s[12:13]
	s_waitcnt vmcnt(15)
	v_mul_f32_e32 v32, 0xbfb8aa3b, v16
	v_exp_f32_e32 v32, v32
	s_nop 0
	v_add_f32_e32 v32, 1.0, v32
	v_rcp_f32_e32 v32, v32
	s_nop 0
	v_mul_f32_e32 v16, v16, v32
	ds_write_b32 v2, v16
	s_waitcnt vmcnt(14)
	v_mul_f32_e32 v32, 0xbfb8aa3b, v17
	v_exp_f32_e32 v32, v32
	s_nop 0
	v_add_f32_e32 v32, 1.0, v32
	v_rcp_f32_e32 v32, v32
	s_nop 0
	v_mul_f32_e32 v17, v17, v32
	ds_write_b32 v2, v17 offset:2048
	s_waitcnt vmcnt(13)
	v_mul_f32_e32 v32, 0xbfb8aa3b, v18
	v_exp_f32_e32 v32, v32
	s_nop 0
	v_add_f32_e32 v32, 1.0, v32
	v_rcp_f32_e32 v32, v32
	s_nop 0
	v_mul_f32_e32 v18, v18, v32
	ds_write_b32 v2, v18 offset:4096
	s_waitcnt vmcnt(12)
	v_mul_f32_e32 v32, 0xbfb8aa3b, v19
	v_exp_f32_e32 v32, v32
	s_nop 0
	v_add_f32_e32 v32, 1.0, v32
	v_rcp_f32_e32 v32, v32
	s_nop 0
	v_mul_f32_e32 v19, v19, v32
	ds_write_b32 v2, v19 offset:6144
	s_waitcnt vmcnt(11)
	v_mul_f32_e32 v32, 0xbfb8aa3b, v20
	v_exp_f32_e32 v32, v32
	s_nop 0
	v_add_f32_e32 v32, 1.0, v32
	v_rcp_f32_e32 v32, v32
	s_nop 0
	v_mul_f32_e32 v20, v20, v32
	ds_write_b32 v2, v20 offset:8192
	s_waitcnt vmcnt(10)
	v_mul_f32_e32 v32, 0xbfb8aa3b, v21
	v_exp_f32_e32 v32, v32
	s_nop 0
	v_add_f32_e32 v32, 1.0, v32
	v_rcp_f32_e32 v32, v32
	s_nop 0
	v_mul_f32_e32 v21, v21, v32
	ds_write_b32 v2, v21 offset:10240
	s_waitcnt vmcnt(9)
	v_mul_f32_e32 v32, 0xbfb8aa3b, v22
	v_exp_f32_e32 v32, v32
	s_nop 0
	v_add_f32_e32 v32, 1.0, v32
	v_rcp_f32_e32 v32, v32
	s_nop 0
	v_mul_f32_e32 v22, v22, v32
	ds_write_b32 v2, v22 offset:12288
	s_waitcnt vmcnt(8)
	v_mul_f32_e32 v32, 0xbfb8aa3b, v23
	v_exp_f32_e32 v32, v32
	s_nop 0
	v_add_f32_e32 v32, 1.0, v32
	v_rcp_f32_e32 v32, v32
	s_nop 0
	v_mul_f32_e32 v23, v23, v32
	ds_write_b32 v2, v23 offset:14336
	s_waitcnt vmcnt(7)
	v_mul_f32_e32 v32, 0xbfb8aa3b, v24
	v_exp_f32_e32 v32, v32
	s_nop 0
	v_add_f32_e32 v32, 1.0, v32
	v_rcp_f32_e32 v32, v32
	s_nop 0
	v_mul_f32_e32 v24, v24, v32
	ds_write_b32 v2, v24 offset:16384
	s_waitcnt vmcnt(6)
	v_mul_f32_e32 v32, 0xbfb8aa3b, v25
	v_exp_f32_e32 v32, v32
	s_nop 0
	v_add_f32_e32 v32, 1.0, v32
	v_rcp_f32_e32 v32, v32
	s_nop 0
	v_mul_f32_e32 v25, v25, v32
	ds_write_b32 v2, v25 offset:18432
	s_waitcnt vmcnt(5)
	v_mul_f32_e32 v32, 0xbfb8aa3b, v26
	v_exp_f32_e32 v32, v32
	s_nop 0
	v_add_f32_e32 v32, 1.0, v32
	v_rcp_f32_e32 v32, v32
	s_nop 0
	v_mul_f32_e32 v26, v26, v32
	ds_write_b32 v2, v26 offset:20480
	s_waitcnt vmcnt(4)
	v_mul_f32_e32 v32, 0xbfb8aa3b, v27
	v_exp_f32_e32 v32, v32
	s_nop 0
	v_add_f32_e32 v32, 1.0, v32
	v_rcp_f32_e32 v32, v32
	s_nop 0
	v_mul_f32_e32 v27, v27, v32
	ds_write_b32 v2, v27 offset:22528
	s_waitcnt vmcnt(3)
	v_mul_f32_e32 v32, 0xbfb8aa3b, v28
	v_exp_f32_e32 v32, v32
	s_nop 0
	v_add_f32_e32 v32, 1.0, v32
	v_rcp_f32_e32 v32, v32
	s_nop 0
	v_mul_f32_e32 v28, v28, v32
	ds_write_b32 v2, v28 offset:24576
	s_waitcnt vmcnt(2)
	v_mul_f32_e32 v32, 0xbfb8aa3b, v29
	v_exp_f32_e32 v32, v32
	s_nop 0
	v_add_f32_e32 v32, 1.0, v32
	v_rcp_f32_e32 v32, v32
	s_nop 0
	v_mul_f32_e32 v29, v29, v32
	ds_write_b32 v2, v29 offset:26624
	s_waitcnt vmcnt(1)
	v_mul_f32_e32 v32, 0xbfb8aa3b, v30
	v_exp_f32_e32 v32, v32
	s_nop 0
	v_add_f32_e32 v32, 1.0, v32
	v_rcp_f32_e32 v32, v32
	s_nop 0
	v_mul_f32_e32 v30, v30, v32
	ds_write_b32 v2, v30 offset:28672
	s_waitcnt vmcnt(0)
	v_mul_f32_e32 v32, 0xbfb8aa3b, v31
	v_exp_f32_e32 v32, v32
	s_nop 0
	v_add_f32_e32 v32, 1.0, v32
	v_rcp_f32_e32 v32, v32
	s_nop 0
	v_mul_f32_e32 v31, v31, v32
	ds_write_b32 v2, v31 offset:30720
	v_add_u32_e32 v2, 0x8000, v2
	global_load_dword v16, v[0:1], off
	v_lshl_add_u64 v[0:1], v[0:1], 0, s[12:13]
	global_load_dword v17, v[0:1], off
	v_lshl_add_u64 v[0:1], v[0:1], 0, s[12:13]
	global_load_dword v18, v[0:1], off
	v_lshl_add_u64 v[0:1], v[0:1], 0, s[12:13]
	global_load_dword v19, v[0:1], off
	v_lshl_add_u64 v[0:1], v[0:1], 0, s[12:13]
	global_load_dword v20, v[0:1], off
	v_lshl_add_u64 v[0:1], v[0:1], 0, s[12:13]
	global_load_dword v21, v[0:1], off
	v_lshl_add_u64 v[0:1], v[0:1], 0, s[12:13]
	global_load_dword v22, v[0:1], off
	v_lshl_add_u64 v[0:1], v[0:1], 0, s[12:13]
	global_load_dword v23, v[0:1], off
	v_lshl_add_u64 v[0:1], v[0:1], 0, s[12:13]
	global_load_dword v24, v[0:1], off
	v_lshl_add_u64 v[0:1], v[0:1], 0, s[12:13]
	global_load_dword v25, v[0:1], off
	v_lshl_add_u64 v[0:1], v[0:1], 0, s[12:13]
	global_load_dword v26, v[0:1], off
	v_lshl_add_u64 v[0:1], v[0:1], 0, s[12:13]
	global_load_dword v27, v[0:1], off
	v_lshl_add_u64 v[0:1], v[0:1], 0, s[12:13]
	global_load_dword v28, v[0:1], off
	v_lshl_add_u64 v[0:1], v[0:1], 0, s[12:13]
	global_load_dword v29, v[0:1], off
	v_lshl_add_u64 v[0:1], v[0:1], 0, s[12:13]
	global_load_dword v30, v[0:1], off
	v_lshl_add_u64 v[0:1], v[0:1], 0, s[12:13]
	global_load_dword v31, v[0:1], off
	v_lshl_add_u64 v[0:1], v[0:1], 0, s[12:13]
	s_waitcnt vmcnt(15)
; __device__ __forceinline__ float siluf_(float x) { return x * sigmoidf_(x); }
; __device__ __forceinline__ void p0_phase(LAS unsigned char* lds, const float* c, const float* w_ada, const float* b_ada, const float* w_in, const float* w_out,
;                                          float* mod, bf16* win_t, bf16* wout_t, int tid, int wid, int lane) {
;     ...
;         for (int i = tid; i < 32 * 1024; i += 512) { const float cv = c[i]; cs[i] = siluf_(cv); }
	v_mul_f32_e32 v32, 0xbfb8aa3b, v16
	v_exp_f32_e32 v32, v32
	s_nop 0
	v_add_f32_e32 v32, 1.0, v32
	v_rcp_f32_e32 v32, v32
	s_nop 0
	v_mul_f32_e32 v16, v16, v32
	ds_write_b32 v2, v16
	s_waitcnt vmcnt(14)
	v_mul_f32_e32 v32, 0xbfb8aa3b, v17
	v_exp_f32_e32 v32, v32
	s_nop 0
	v_add_f32_e32 v32, 1.0, v32
	v_rcp_f32_e32 v32, v32
	s_nop 0
	v_mul_f32_e32 v17, v17, v32
	ds_write_b32 v2, v17 offset:2048
	s_waitcnt vmcnt(13)
	v_mul_f32_e32 v32, 0xbfb8aa3b, v18
	v_exp_f32_e32 v32, v32
	s_nop 0
	v_add_f32_e32 v32, 1.0, v32
	v_rcp_f32_e32 v32, v32
	s_nop 0
	v_mul_f32_e32 v18, v18, v32
	ds_write_b32 v2, v18 offset:4096
	s_waitcnt vmcnt(12)
	v_mul_f32_e32 v32, 0xbfb8aa3b, v19
	v_exp_f32_e32 v32, v32
	s_nop 0
	v_add_f32_e32 v32, 1.0, v32
	v_rcp_f32_e32 v32, v32
	s_nop 0
	v_mul_f32_e32 v19, v19, v32
	ds_write_b32 v2, v19 offset:6144
	s_waitcnt vmcnt(11)
	v_mul_f32_e32 v32, 0xbfb8aa3b, v20
	v_exp_f32_e32 v32, v32
	s_nop 0
	v_add_f32_e32 v32, 1.0, v32
	v_rcp_f32_e32 v32, v32
	s_nop 0
	v_mul_f32_e32 v20, v20, v32
	ds_write_b32 v2, v20 offset:8192
	s_waitcnt vmcnt(10)
	v_mul_f32_e32 v32, 0xbfb8aa3b, v21
	v_exp_f32_e32 v32, v32
	s_nop 0
	v_add_f32_e32 v32, 1.0, v32
	v_rcp_f32_e32 v32, v32
	s_nop 0
	v_mul_f32_e32 v21, v21, v32
	ds_write_b32 v2, v21 offset:10240
	s_waitcnt vmcnt(9)
	v_mul_f32_e32 v32, 0xbfb8aa3b, v22
	v_exp_f32_e32 v32, v32
	s_nop 0
	v_add_f32_e32 v32, 1.0, v32
	v_rcp_f32_e32 v32, v32
	s_nop 0
	v_mul_f32_e32 v22, v22, v32
	ds_write_b32 v2, v22 offset:12288
	s_waitcnt vmcnt(8)
	v_mul_f32_e32 v32, 0xbfb8aa3b, v23
	v_exp_f32_e32 v32, v32
	s_nop 0
	v_add_f32_e32 v32, 1.0, v32
	v_rcp_f32_e32 v32, v32
	s_nop 0
	v_mul_f32_e32 v23, v23, v32
	ds_write_b32 v2, v23 offset:14336
	s_waitcnt vmcnt(7)
	v_mul_f32_e32 v32, 0xbfb8aa3b, v24
	v_exp_f32_e32 v32, v32
	s_nop 0
	v_add_f32_e32 v32, 1.0, v32
	v_rcp_f32_e32 v32, v32
	s_nop 0
	v_mul_f32_e32 v24, v24, v32
	ds_write_b32 v2, v24 offset:16384
	s_waitcnt vmcnt(6)
	v_mul_f32_e32 v32, 0xbfb8aa3b, v25
	v_exp_f32_e32 v32, v32
	s_nop 0
	v_add_f32_e32 v32, 1.0, v32
	v_rcp_f32_e32 v32, v32
	s_nop 0
	v_mul_f32_e32 v25, v25, v32
	ds_write_b32 v2, v25 offset:18432
	s_waitcnt vmcnt(5)
	v_mul_f32_e32 v32, 0xbfb8aa3b, v26
	v_exp_f32_e32 v32, v32
	s_nop 0
	v_add_f32_e32 v32, 1.0, v32
	v_rcp_f32_e32 v32, v32
	s_nop 0
	v_mul_f32_e32 v26, v26, v32
	ds_write_b32 v2, v26 offset:20480
	s_waitcnt vmcnt(4)
	v_mul_f32_e32 v32, 0xbfb8aa3b, v27
	v_exp_f32_e32 v32, v32
	s_nop 0
	v_add_f32_e32 v32, 1.0, v32
	v_rcp_f32_e32 v32, v32
	s_nop 0
	v_mul_f32_e32 v27, v27, v32
	ds_write_b32 v2, v27 offset:22528
	s_waitcnt vmcnt(3)
	v_mul_f32_e32 v32, 0xbfb8aa3b, v28
	v_exp_f32_e32 v32, v32
	s_nop 0
	v_add_f32_e32 v32, 1.0, v32
	v_rcp_f32_e32 v32, v32
	s_nop 0
	v_mul_f32_e32 v28, v28, v32
	ds_write_b32 v2, v28 offset:24576
	s_waitcnt vmcnt(2)
	v_mul_f32_e32 v32, 0xbfb8aa3b, v29
	v_exp_f32_e32 v32, v32
	s_nop 0
	v_add_f32_e32 v32, 1.0, v32
	v_rcp_f32_e32 v32, v32
	s_nop 0
	v_mul_f32_e32 v29, v29, v32
	ds_write_b32 v2, v29 offset:26624
	s_waitcnt vmcnt(1)
	v_mul_f32_e32 v32, 0xbfb8aa3b, v30
	v_exp_f32_e32 v32, v32
	s_nop 0
	v_add_f32_e32 v32, 1.0, v32
	v_rcp_f32_e32 v32, v32
	s_nop 0
	v_mul_f32_e32 v30, v30, v32
	ds_write_b32 v2, v30 offset:28672
	s_waitcnt vmcnt(0)
	v_mul_f32_e32 v32, 0xbfb8aa3b, v31
	v_exp_f32_e32 v32, v32
	s_nop 0
	v_add_f32_e32 v32, 1.0, v32
	v_rcp_f32_e32 v32, v32
	s_nop 0
	v_mul_f32_e32 v31, v31, v32
	ds_write_b32 v2, v31 offset:30720
	v_add_u32_e32 v2, 0x8000, v2
	global_load_dword v16, v[0:1], off
	v_lshl_add_u64 v[0:1], v[0:1], 0, s[12:13]
	global_load_dword v17, v[0:1], off
	v_lshl_add_u64 v[0:1], v[0:1], 0, s[12:13]
	global_load_dword v18, v[0:1], off
	v_lshl_add_u64 v[0:1], v[0:1], 0, s[12:13]
	global_load_dword v19, v[0:1], off
	v_lshl_add_u64 v[0:1], v[0:1], 0, s[12:13]
	global_load_dword v20, v[0:1], off
	v_lshl_add_u64 v[0:1], v[0:1], 0, s[12:13]
	global_load_dword v21, v[0:1], off
	v_lshl_add_u64 v[0:1], v[0:1], 0, s[12:13]
	global_load_dword v22, v[0:1], off
	v_lshl_add_u64 v[0:1], v[0:1], 0, s[12:13]
	global_load_dword v23, v[0:1], off
	v_lshl_add_u64 v[0:1], v[0:1], 0, s[12:13]
	global_load_dword v24, v[0:1], off
	v_lshl_add_u64 v[0:1], v[0:1], 0, s[12:13]
	global_load_dword v25, v[0:1], off
	v_lshl_add_u64 v[0:1], v[0:1], 0, s[12:13]
	global_load_dword v26, v[0:1], off
	v_lshl_add_u64 v[0:1], v[0:1], 0, s[12:13]
	global_load_dword v27, v[0:1], off
	v_lshl_add_u64 v[0:1], v[0:1], 0, s[12:13]
	global_load_dword v28, v[0:1], off
	v_lshl_add_u64 v[0:1], v[0:1], 0, s[12:13]
	global_load_dword v29, v[0:1], off
	v_lshl_add_u64 v[0:1], v[0:1], 0, s[12:13]
	global_load_dword v30, v[0:1], off
	v_lshl_add_u64 v[0:1], v[0:1], 0, s[12:13]
	global_load_dword v31, v[0:1], off
	v_lshl_add_u64 v[0:1], v[0:1], 0, s[12:13]
	s_waitcnt vmcnt(15)
	v_mul_f32_e32 v32, 0xbfb8aa3b, v16
	v_exp_f32_e32 v32, v32
	s_nop 0
	v_add_f32_e32 v32, 1.0, v32
	v_rcp_f32_e32 v32, v32
	s_nop 0
	v_mul_f32_e32 v16, v16, v32
	ds_write_b32 v2, v16
	s_waitcnt vmcnt(14)
	v_mul_f32_e32 v32, 0xbfb8aa3b, v17
	v_exp_f32_e32 v32, v32
	s_nop 0
	v_add_f32_e32 v32, 1.0, v32
	v_rcp_f32_e32 v32, v32
	s_nop 0
	v_mul_f32_e32 v17, v17, v32
	ds_write_b32 v2, v17 offset:2048
	s_waitcnt vmcnt(13)
	v_mul_f32_e32 v32, 0xbfb8aa3b, v18
	v_exp_f32_e32 v32, v32
	s_nop 0
	v_add_f32_e32 v32, 1.0, v32
	v_rcp_f32_e32 v32, v32
	s_nop 0
	v_mul_f32_e32 v18, v18, v32
	ds_write_b32 v2, v18 offset:4096
	s_waitcnt vmcnt(12)
	v_mul_f32_e32 v32, 0xbfb8aa3b, v19
	v_exp_f32_e32 v32, v32
	s_nop 0
	v_add_f32_e32 v32, 1.0, v32
	v_rcp_f32_e32 v32, v32
	s_nop 0
	v_mul_f32_e32 v19, v19, v32
	ds_write_b32 v2, v19 offset:6144
	s_waitcnt vmcnt(11)
; __device__ __forceinline__ float siluf_(float x) { return x * sigmoidf_(x); }
; __device__ __forceinline__ void p0_phase(LAS unsigned char* lds, const float* c, const float* w_ada, const float* b_ada, const float* w_in, const float* w_out,
;                                          float* mod, bf16* win_t, bf16* wout_t, int tid, int wid, int lane) {
;     ...
;         for (int i = tid; i < 32 * 1024; i += 512) { const float cv = c[i]; cs[i] = siluf_(cv); }
	v_mul_f32_e32 v32, 0xbfb8aa3b, v20
	v_exp_f32_e32 v32, v32
	s_nop 0
	v_add_f32_e32 v32, 1.0, v32
	v_rcp_f32_e32 v32, v32
	s_nop 0
	v_mul_f32_e32 v20, v20, v32
	ds_write_b32 v2, v20 offset:8192
	s_waitcnt vmcnt(10)
	v_mul_f32_e32 v32, 0xbfb8aa3b, v21
	v_exp_f32_e32 v32, v32
	s_nop 0
	v_add_f32_e32 v32, 1.0, v32
	v_rcp_f32_e32 v32, v32
	s_nop 0
	v_mul_f32_e32 v21, v21, v32
	ds_write_b32 v2, v21 offset:10240
	s_waitcnt vmcnt(9)
	v_mul_f32_e32 v32, 0xbfb8aa3b, v22
	v_exp_f32_e32 v32, v32
	s_nop 0
	v_add_f32_e32 v32, 1.0, v32
	v_rcp_f32_e32 v32, v32
	s_nop 0
	v_mul_f32_e32 v22, v22, v32
	ds_write_b32 v2, v22 offset:12288
	s_waitcnt vmcnt(8)
	v_mul_f32_e32 v32, 0xbfb8aa3b, v23
	v_exp_f32_e32 v32, v32
	s_nop 0
	v_add_f32_e32 v32, 1.0, v32
	v_rcp_f32_e32 v32, v32
	s_nop 0
	v_mul_f32_e32 v23, v23, v32
	ds_write_b32 v2, v23 offset:14336
	s_waitcnt vmcnt(7)
	v_mul_f32_e32 v32, 0xbfb8aa3b, v24
	v_exp_f32_e32 v32, v32
	s_nop 0
	v_add_f32_e32 v32, 1.0, v32
	v_rcp_f32_e32 v32, v32
	s_nop 0
	v_mul_f32_e32 v24, v24, v32
	ds_write_b32 v2, v24 offset:16384
	s_waitcnt vmcnt(6)
	v_mul_f32_e32 v32, 0xbfb8aa3b, v25
	v_exp_f32_e32 v32, v32
	s_nop 0
	v_add_f32_e32 v32, 1.0, v32
	v_rcp_f32_e32 v32, v32
	s_nop 0
	v_mul_f32_e32 v25, v25, v32
	ds_write_b32 v2, v25 offset:18432
	s_waitcnt vmcnt(5)
	v_mul_f32_e32 v32, 0xbfb8aa3b, v26
	v_exp_f32_e32 v32, v32
	s_nop 0
	v_add_f32_e32 v32, 1.0, v32
	v_rcp_f32_e32 v32, v32
	s_nop 0
	v_mul_f32_e32 v26, v26, v32
	ds_write_b32 v2, v26 offset:20480
	s_waitcnt vmcnt(4)
	v_mul_f32_e32 v32, 0xbfb8aa3b, v27
	v_exp_f32_e32 v32, v32
	s_nop 0
	v_add_f32_e32 v32, 1.0, v32
	v_rcp_f32_e32 v32, v32
	s_nop 0
	v_mul_f32_e32 v27, v27, v32
	ds_write_b32 v2, v27 offset:22528
	s_waitcnt vmcnt(3)
	v_mul_f32_e32 v32, 0xbfb8aa3b, v28
	v_exp_f32_e32 v32, v32
	s_nop 0
	v_add_f32_e32 v32, 1.0, v32
	v_rcp_f32_e32 v32, v32
	s_nop 0
	v_mul_f32_e32 v28, v28, v32
	ds_write_b32 v2, v28 offset:24576
	s_waitcnt vmcnt(2)
	v_mul_f32_e32 v32, 0xbfb8aa3b, v29
	v_exp_f32_e32 v32, v32
	s_nop 0
	v_add_f32_e32 v32, 1.0, v32
	v_rcp_f32_e32 v32, v32
	s_nop 0
	v_mul_f32_e32 v29, v29, v32
	ds_write_b32 v2, v29 offset:26624
	s_waitcnt vmcnt(1)
	v_mul_f32_e32 v32, 0xbfb8aa3b, v30
	v_exp_f32_e32 v32, v32
	s_nop 0
	v_add_f32_e32 v32, 1.0, v32
	v_rcp_f32_e32 v32, v32
	s_nop 0
	v_mul_f32_e32 v30, v30, v32
	ds_write_b32 v2, v30 offset:28672
	s_waitcnt vmcnt(0)
	v_mul_f32_e32 v32, 0xbfb8aa3b, v31
	v_exp_f32_e32 v32, v32
	s_nop 0
	v_add_f32_e32 v32, 1.0, v32
	v_rcp_f32_e32 v32, v32
	s_nop 0
	v_mul_f32_e32 v31, v31, v32
	ds_write_b32 v2, v31 offset:30720
	v_add_u32_e32 v2, 0x8000, v2
	global_load_dword v16, v[0:1], off
	v_lshl_add_u64 v[0:1], v[0:1], 0, s[12:13]
	global_load_dword v17, v[0:1], off
	v_lshl_add_u64 v[0:1], v[0:1], 0, s[12:13]
	global_load_dword v18, v[0:1], off
	v_lshl_add_u64 v[0:1], v[0:1], 0, s[12:13]
	global_load_dword v19, v[0:1], off
	v_lshl_add_u64 v[0:1], v[0:1], 0, s[12:13]
	global_load_dword v20, v[0:1], off
	v_lshl_add_u64 v[0:1], v[0:1], 0, s[12:13]
	global_load_dword v21, v[0:1], off
	v_lshl_add_u64 v[0:1], v[0:1], 0, s[12:13]
	global_load_dword v22, v[0:1], off
	v_lshl_add_u64 v[0:1], v[0:1], 0, s[12:13]
	global_load_dword v23, v[0:1], off
	v_lshl_add_u64 v[0:1], v[0:1], 0, s[12:13]
	global_load_dword v24, v[0:1], off
	v_lshl_add_u64 v[0:1], v[0:1], 0, s[12:13]
	global_load_dword v25, v[0:1], off
	v_lshl_add_u64 v[0:1], v[0:1], 0, s[12:13]
	global_load_dword v26, v[0:1], off
	v_lshl_add_u64 v[0:1], v[0:1], 0, s[12:13]
	global_load_dword v27, v[0:1], off
	v_lshl_add_u64 v[0:1], v[0:1], 0, s[12:13]
	global_load_dword v28, v[0:1], off
	v_lshl_add_u64 v[0:1], v[0:1], 0, s[12:13]
	global_load_dword v29, v[0:1], off
	v_lshl_add_u64 v[0:1], v[0:1], 0, s[12:13]
	global_load_dword v30, v[0:1], off
	v_lshl_add_u64 v[0:1], v[0:1], 0, s[12:13]
	global_load_dword v31, v[0:1], off
	v_lshl_add_u64 v[0:1], v[0:1], 0, s[12:13]
	s_waitcnt vmcnt(15)
	v_mul_f32_e32 v32, 0xbfb8aa3b, v16
	v_exp_f32_e32 v32, v32
	s_nop 0
	v_add_f32_e32 v32, 1.0, v32
	v_rcp_f32_e32 v32, v32
	s_nop 0
	v_mul_f32_e32 v16, v16, v32
	ds_write_b32 v2, v16
	s_waitcnt vmcnt(14)
	v_mul_f32_e32 v32, 0xbfb8aa3b, v17
	v_exp_f32_e32 v32, v32
	s_nop 0
	v_add_f32_e32 v32, 1.0, v32
	v_rcp_f32_e32 v32, v32
	s_nop 0
	v_mul_f32_e32 v17, v17, v32
	ds_write_b32 v2, v17 offset:2048
	s_waitcnt vmcnt(13)
	v_mul_f32_e32 v32, 0xbfb8aa3b, v18
	v_exp_f32_e32 v32, v32
	s_nop 0
	v_add_f32_e32 v32, 1.0, v32
	v_rcp_f32_e32 v32, v32
	s_nop 0
	v_mul_f32_e32 v18, v18, v32
	ds_write_b32 v2, v18 offset:4096
	s_waitcnt vmcnt(12)
	v_mul_f32_e32 v32, 0xbfb8aa3b, v19
	v_exp_f32_e32 v32, v32
	s_nop 0
	v_add_f32_e32 v32, 1.0, v32
	v_rcp_f32_e32 v32, v32
	s_nop 0
	v_mul_f32_e32 v19, v19, v32
	ds_write_b32 v2, v19 offset:6144
	s_waitcnt vmcnt(11)
	v_mul_f32_e32 v32, 0xbfb8aa3b, v20
	v_exp_f32_e32 v32, v32
	s_nop 0
	v_add_f32_e32 v32, 1.0, v32
	v_rcp_f32_e32 v32, v32
	s_nop 0
	v_mul_f32_e32 v20, v20, v32
	ds_write_b32 v2, v20 offset:8192
	s_waitcnt vmcnt(10)
	v_mul_f32_e32 v32, 0xbfb8aa3b, v21
	v_exp_f32_e32 v32, v32
	s_nop 0
	v_add_f32_e32 v32, 1.0, v32
	v_rcp_f32_e32 v32, v32
	s_nop 0
	v_mul_f32_e32 v21, v21, v32
	ds_write_b32 v2, v21 offset:10240
	s_waitcnt vmcnt(9)
	v_mul_f32_e32 v32, 0xbfb8aa3b, v22
	v_exp_f32_e32 v32, v32
	s_nop 0
	v_add_f32_e32 v32, 1.0, v32
	v_rcp_f32_e32 v32, v32
	s_nop 0
	v_mul_f32_e32 v22, v22, v32
	ds_write_b32 v2, v22 offset:12288
	s_waitcnt vmcnt(8)
	v_mul_f32_e32 v32, 0xbfb8aa3b, v23
	v_exp_f32_e32 v32, v32
	s_nop 0
	v_add_f32_e32 v32, 1.0, v32
	v_rcp_f32_e32 v32, v32
	s_nop 0
	v_mul_f32_e32 v23, v23, v32
	ds_write_b32 v2, v23 offset:14336
	s_waitcnt vmcnt(7)
; #define LAS __attribute__((address_space(3)))
; __device__ __forceinline__ float siluf_(float x) { return x * sigmoidf_(x); }
; __device__ __forceinline__ void p0_phase(LAS unsigned char* lds, const float* c, const float* w_ada, const float* b_ada, const float* w_in, const float* w_out,
;                                          float* mod, bf16* win_t, bf16* wout_t, int tid, int wid, int lane) {
;     ...
;         for (int i = tid; i < 32 * 1024; i += 512) { const float cv = c[i]; cs[i] = siluf_(cv); }
;         __syncthreads();
;         const int n = nb * 64 + lane, kbase = wid * 128;
;         const float* wp = w_ada + (size_t)l * 1024 * 3072 + (size_t)kbase * 3072 + n;
;         float acc[32];
; #pragma unroll
;         for (int b = 0; b < 32; ++b) acc[b] = 0.f;
; #pragma unroll 2
;         for (int k = 0; k < 128; k += 4) {
;             const float w0 = wp[(size_t)k * 3072], w1 = wp[(size_t)(k + 1) * 3072], w2 = wp[(size_t)(k + 2) * 3072], w3 = wp[(size_t)(k + 3) * 3072];
; #pragma unroll
;             for (int b = 0; b < 32; ++b) { const f32x4 cv = *(const LAS f32x4*)(cs + b * 1024 + kbase + k); acc[b] += cv[0] * w0 + cv[1] * w1 + cv[2] * w2 + cv[3] * w3; }
	v_mul_f32_e32 v32, 0xbfb8aa3b, v24
	v_exp_f32_e32 v32, v32
	s_nop 0
	v_add_f32_e32 v32, 1.0, v32
	v_rcp_f32_e32 v32, v32
	s_nop 0
	v_mul_f32_e32 v24, v24, v32
	ds_write_b32 v2, v24 offset:16384
	s_waitcnt vmcnt(6)
	v_mul_f32_e32 v32, 0xbfb8aa3b, v25
	v_exp_f32_e32 v32, v32
	s_nop 0
	v_add_f32_e32 v32, 1.0, v32
	v_rcp_f32_e32 v32, v32
	s_nop 0
	v_mul_f32_e32 v25, v25, v32
	ds_write_b32 v2, v25 offset:18432
	s_waitcnt vmcnt(5)
	v_mul_f32_e32 v32, 0xbfb8aa3b, v26
	v_exp_f32_e32 v32, v32
	s_nop 0
	v_add_f32_e32 v32, 1.0, v32
	v_rcp_f32_e32 v32, v32
	s_nop 0
	v_mul_f32_e32 v26, v26, v32
	ds_write_b32 v2, v26 offset:20480
	s_waitcnt vmcnt(4)
	v_mul_f32_e32 v32, 0xbfb8aa3b, v27
	v_exp_f32_e32 v32, v32
	s_nop 0
	v_add_f32_e32 v32, 1.0, v32
	v_rcp_f32_e32 v32, v32
	s_nop 0
	v_mul_f32_e32 v27, v27, v32
	ds_write_b32 v2, v27 offset:22528
	s_waitcnt vmcnt(3)
	v_mul_f32_e32 v32, 0xbfb8aa3b, v28
	v_exp_f32_e32 v32, v32
	s_nop 0
	v_add_f32_e32 v32, 1.0, v32
	v_rcp_f32_e32 v32, v32
	s_nop 0
	v_mul_f32_e32 v28, v28, v32
	ds_write_b32 v2, v28 offset:24576
	s_waitcnt vmcnt(2)
	v_mul_f32_e32 v32, 0xbfb8aa3b, v29
	v_exp_f32_e32 v32, v32
	s_nop 0
	v_add_f32_e32 v32, 1.0, v32
	v_rcp_f32_e32 v32, v32
	s_nop 0
	v_mul_f32_e32 v29, v29, v32
	ds_write_b32 v2, v29 offset:26624
	s_waitcnt vmcnt(1)
	v_mul_f32_e32 v32, 0xbfb8aa3b, v30
	v_exp_f32_e32 v32, v32
	s_nop 0
	v_add_f32_e32 v32, 1.0, v32
	v_rcp_f32_e32 v32, v32
	s_nop 0
	v_mul_f32_e32 v30, v30, v32
	ds_write_b32 v2, v30 offset:28672
	s_waitcnt vmcnt(0)
	v_mul_f32_e32 v32, 0xbfb8aa3b, v31
	v_exp_f32_e32 v32, v32
	s_nop 0
	v_add_f32_e32 v32, 1.0, v32
	v_rcp_f32_e32 v32, v32
	s_nop 0
	v_mul_f32_e32 v31, v31, v32
	ds_write_b32 v2, v31 offset:30720
	v_add_u32_e32 v2, 0x8000, v2
	s_or_b64 exec, exec, s[16:17]
	s_mul_hi_i32 s16, s31, 0x2aaaaaab
	s_lshr_b32 s17, s16, 31
	s_ashr_i32 s16, s16, 3
	s_add_i32 s16, s16, s17
	s_ashr_i32 s17, s16, 31
	s_mul_i32 s34, s16, 0xc00000
	v_lshl_or_b32 v0, s31, 6, v203
	s_mul_i32 s33, s16, 0xc00
	s_mul_hi_i32 s35, s16, 0xc00000
	v_subrev_u32_e32 v0, s33, v0
	s_add_u32 s34, s21, s34
	v_ashrrev_i32_e32 v1, 31, v0
	s_addc_u32 s35, s22, s35
	v_mov_b32_e32 v34, 0
	v_lshl_add_u64 v[16:17], v[0:1], 2, s[34:35]
	s_mov_b32 s34, -4
	s_mov_b32 s35, s18
	v_mov_b32_e32 v35, v34
	v_mov_b32_e32 v18, v34
	v_mov_b32_e32 v19, v34
	v_mov_b32_e32 v20, v34
	v_mov_b32_e32 v21, v34
	v_mov_b32_e32 v22, v34
	v_mov_b32_e32 v23, v34
	v_mov_b32_e32 v24, v34
	v_mov_b32_e32 v25, v34
	v_mov_b32_e32 v26, v34
	v_mov_b32_e32 v27, v34
	v_mov_b32_e32 v28, v34
	v_mov_b32_e32 v29, v34
	v_mov_b32_e32 v30, v34
	v_mov_b32_e32 v31, v34
	v_mov_b32_e32 v32, v34
	v_mov_b32_e32 v33, v34
	v_mov_b32_e32 v52, v34
	v_mov_b32_e32 v53, v34
	v_mov_b32_e32 v54, v34
	v_mov_b32_e32 v55, v34
	v_mov_b32_e32 v56, v34
	v_mov_b32_e32 v57, v34
	v_mov_b32_e32 v50, v34
	v_mov_b32_e32 v51, v34
	v_mov_b32_e32 v48, v34
	v_mov_b32_e32 v49, v34
	v_mov_b32_e32 v46, v34
	v_mov_b32_e32 v47, v34
	v_mov_b32_e32 v44, v34
	v_mov_b32_e32 v45, v34
	s_waitcnt lgkmcnt(0)
	s_barrier
	s_mov_b32 s48, 0x3000
	s_mov_b32 s49, 0
	s_mov_b32 s52, 8
	v_add_co_u32_e32 v92, vcc, s24, v16
	s_nop 1
	v_addc_co_u32_e32 v93, vcc, -1, v17, vcc
	global_load_dword v76, v[92:93], off
	v_lshl_add_u64 v[92:93], v[92:93], 0, s[48:49]
	global_load_dword v77, v[92:93], off
	v_lshl_add_u64 v[92:93], v[92:93], 0, s[48:49]
	global_load_dword v78, v[92:93], off
	v_lshl_add_u64 v[92:93], v[92:93], 0, s[48:49]
	global_load_dword v79, v[92:93], off
	v_lshl_add_u64 v[92:93], v[92:93], 0, s[48:49]
	global_load_dword v80, v[92:93], off
	v_lshl_add_u64 v[92:93], v[92:93], 0, s[48:49]
	global_load_dword v81, v[92:93], off
	v_lshl_add_u64 v[92:93], v[92:93], 0, s[48:49]
	global_load_dword v82, v[92:93], off
	v_lshl_add_u64 v[92:93], v[92:93], 0, s[48:49]
	global_load_dword v83, v[92:93], off
	v_lshl_add_u64 v[16:17], v[16:17], 0, s[14:15]
.LBB0_21:
	v_mov_b32_e32 v94, s35
	s_add_i32 s36, s35, 0x10000
	v_mov_b32_e32 v95, s36
	v_add_co_u32_e32 v92, vcc, s24, v16
	s_nop 1
	v_addc_co_u32_e32 v93, vcc, -1, v17, vcc
	global_load_dword v84, v[92:93], off
	v_lshl_add_u64 v[92:93], v[92:93], 0, s[48:49]
	global_load_dword v85, v[92:93], off
	v_lshl_add_u64 v[92:93], v[92:93], 0, s[48:49]
	global_load_dword v86, v[92:93], off
	v_lshl_add_u64 v[92:93], v[92:93], 0, s[48:49]
	global_load_dword v87, v[92:93], off
	v_lshl_add_u64 v[92:93], v[92:93], 0, s[48:49]
	global_load_dword v88, v[92:93], off
	v_lshl_add_u64 v[92:93], v[92:93], 0, s[48:49]
	global_load_dword v89, v[92:93], off
	v_lshl_add_u64 v[92:93], v[92:93], 0, s[48:49]
	global_load_dword v90, v[92:93], off
	v_lshl_add_u64 v[92:93], v[92:93], 0, s[48:49]
	global_load_dword v91, v[92:93], off
	v_lshl_add_u64 v[16:17], v[16:17], 0, s[14:15]
	s_waitcnt vmcnt(8)
	ds_read_b128 v[96:99], v94 offset:0
	ds_read_b128 v[100:103], v94 offset:16
	ds_read_b128 v[104:107], v94 offset:4096
	ds_read_b128 v[108:111], v94 offset:4112
	ds_read_b128 v[112:115], v94 offset:8192
	ds_read_b128 v[116:119], v94 offset:8208
	ds_read_b128 v[120:123], v94 offset:12288
	ds_read_b128 v[124:127], v94 offset:12304
	s_waitcnt lgkmcnt(6)
	v_fmac_f32_e32 v18, v76, v96
	v_fmac_f32_e32 v18, v77, v97
	v_fmac_f32_e32 v18, v78, v98
	v_fmac_f32_e32 v18, v79, v99
	v_fmac_f32_e32 v18, v80, v100
	v_fmac_f32_e32 v18, v81, v101
	v_fmac_f32_e32 v18, v82, v102
	v_fmac_f32_e32 v18, v83, v103
	ds_read_b128 v[96:99], v94 offset:16384
	ds_read_b128 v[100:103], v94 offset:16400
	s_waitcnt lgkmcnt(6)
	v_fmac_f32_e32 v19, v76, v104
	v_fmac_f32_e32 v19, v77, v105
	v_fmac_f32_e32 v19, v78, v106
	v_fmac_f32_e32 v19, v79, v107
	v_fmac_f32_e32 v19, v80, v108
	v_fmac_f32_e32 v19, v81, v109
	v_fmac_f32_e32 v19, v82, v110
	v_fmac_f32_e32 v19, v83, v111
	ds_read_b128 v[104:107], v94 offset:20480
	ds_read_b128 v[108:111], v94 offset:20496
	s_waitcnt lgkmcnt(6)
; #define LAS __attribute__((address_space(3)))
; __device__ __forceinline__ void p0_phase(LAS unsigned char* lds, const float* c, const float* w_ada, const float* b_ada, const float* w_in, const float* w_out,
;                                          float* mod, bf16* win_t, bf16* wout_t, int tid, int wid, int lane) {
;     ...
;         for (int k = 0; k < 128; k += 4) {
;             const float w0 = wp[(size_t)k * 3072], w1 = wp[(size_t)(k + 1) * 3072], w2 = wp[(size_t)(k + 2) * 3072], w3 = wp[(size_t)(k + 3) * 3072];
; #pragma unroll
;             for (int b = 0; b < 32; ++b) { const f32x4 cv = *(const LAS f32x4*)(cs + b * 1024 + kbase + k); acc[b] += cv[0] * w0 + cv[1] * w1 + cv[2] * w2 + cv[3] * w3; }
;         }
	v_fmac_f32_e32 v20, v76, v112
	v_fmac_f32_e32 v20, v77, v113
	v_fmac_f32_e32 v20, v78, v114
	v_fmac_f32_e32 v20, v79, v115
	v_fmac_f32_e32 v20, v80, v116
	v_fmac_f32_e32 v20, v81, v117
	v_fmac_f32_e32 v20, v82, v118
	v_fmac_f32_e32 v20, v83, v119
	ds_read_b128 v[112:115], v94 offset:24576
	ds_read_b128 v[116:119], v94 offset:24592
	s_waitcnt lgkmcnt(6)
	v_fmac_f32_e32 v21, v76, v120
	v_fmac_f32_e32 v21, v77, v121
	v_fmac_f32_e32 v21, v78, v122
	v_fmac_f32_e32 v21, v79, v123
	v_fmac_f32_e32 v21, v80, v124
	v_fmac_f32_e32 v21, v81, v125
	v_fmac_f32_e32 v21, v82, v126
	v_fmac_f32_e32 v21, v83, v127
	ds_read_b128 v[120:123], v94 offset:28672
	ds_read_b128 v[124:127], v94 offset:28688
	s_waitcnt lgkmcnt(6)
	v_fmac_f32_e32 v22, v76, v96
	v_fmac_f32_e32 v22, v77, v97
	v_fmac_f32_e32 v22, v78, v98
	v_fmac_f32_e32 v22, v79, v99
	v_fmac_f32_e32 v22, v80, v100
	v_fmac_f32_e32 v22, v81, v101
	v_fmac_f32_e32 v22, v82, v102
	v_fmac_f32_e32 v22, v83, v103
	ds_read_b128 v[96:99], v94 offset:32768
	ds_read_b128 v[100:103], v94 offset:32784
	s_waitcnt lgkmcnt(6)
	v_fmac_f32_e32 v23, v76, v104
	v_fmac_f32_e32 v23, v77, v105
	v_fmac_f32_e32 v23, v78, v106
	v_fmac_f32_e32 v23, v79, v107
	v_fmac_f32_e32 v23, v80, v108
	v_fmac_f32_e32 v23, v81, v109
	v_fmac_f32_e32 v23, v82, v110
	v_fmac_f32_e32 v23, v83, v111
	ds_read_b128 v[104:107], v94 offset:36864
	ds_read_b128 v[108:111], v94 offset:36880
	s_waitcnt lgkmcnt(6)
	v_fmac_f32_e32 v24, v76, v112
	v_fmac_f32_e32 v24, v77, v113
	v_fmac_f32_e32 v24, v78, v114
	v_fmac_f32_e32 v24, v79, v115
	v_fmac_f32_e32 v24, v80, v116
	v_fmac_f32_e32 v24, v81, v117
	v_fmac_f32_e32 v24, v82, v118
	v_fmac_f32_e32 v24, v83, v119
	ds_read_b128 v[112:115], v94 offset:40960
	ds_read_b128 v[116:119], v94 offset:40976
	s_waitcnt lgkmcnt(6)
	v_fmac_f32_e32 v25, v76, v120
	v_fmac_f32_e32 v25, v77, v121
	v_fmac_f32_e32 v25, v78, v122
	v_fmac_f32_e32 v25, v79, v123
	v_fmac_f32_e32 v25, v80, v124
	v_fmac_f32_e32 v25, v81, v125
	v_fmac_f32_e32 v25, v82, v126
	v_fmac_f32_e32 v25, v83, v127
	ds_read_b128 v[120:123], v94 offset:45056
	ds_read_b128 v[124:127], v94 offset:45072
	s_waitcnt lgkmcnt(6)
	v_fmac_f32_e32 v26, v76, v96
	v_fmac_f32_e32 v26, v77, v97
	v_fmac_f32_e32 v26, v78, v98
	v_fmac_f32_e32 v26, v79, v99
	v_fmac_f32_e32 v26, v80, v100
	v_fmac_f32_e32 v26, v81, v101
	v_fmac_f32_e32 v26, v82, v102
	v_fmac_f32_e32 v26, v83, v103
	ds_read_b128 v[96:99], v94 offset:49152
	ds_read_b128 v[100:103], v94 offset:49168
	s_waitcnt lgkmcnt(6)
	v_fmac_f32_e32 v27, v76, v104
	v_fmac_f32_e32 v27, v77, v105
	v_fmac_f32_e32 v27, v78, v106
	v_fmac_f32_e32 v27, v79, v107
	v_fmac_f32_e32 v27, v80, v108
	v_fmac_f32_e32 v27, v81, v109
	v_fmac_f32_e32 v27, v82, v110
	v_fmac_f32_e32 v27, v83, v111
	ds_read_b128 v[104:107], v94 offset:53248
	ds_read_b128 v[108:111], v94 offset:53264
	s_waitcnt lgkmcnt(6)
	v_fmac_f32_e32 v28, v76, v112
	v_fmac_f32_e32 v28, v77, v113
	v_fmac_f32_e32 v28, v78, v114
	v_fmac_f32_e32 v28, v79, v115
	v_fmac_f32_e32 v28, v80, v116
	v_fmac_f32_e32 v28, v81, v117
	v_fmac_f32_e32 v28, v82, v118
	v_fmac_f32_e32 v28, v83, v119
	ds_read_b128 v[112:115], v94 offset:57344
	ds_read_b128 v[116:119], v94 offset:57360
	s_waitcnt lgkmcnt(6)
	v_fmac_f32_e32 v29, v76, v120
	v_fmac_f32_e32 v29, v77, v121
	v_fmac_f32_e32 v29, v78, v122
	v_fmac_f32_e32 v29, v79, v123
	v_fmac_f32_e32 v29, v80, v124
	v_fmac_f32_e32 v29, v81, v125
	v_fmac_f32_e32 v29, v82, v126
	v_fmac_f32_e32 v29, v83, v127
	ds_read_b128 v[120:123], v94 offset:61440
	ds_read_b128 v[124:127], v94 offset:61456
	s_waitcnt lgkmcnt(6)
	v_fmac_f32_e32 v30, v76, v96
	v_fmac_f32_e32 v30, v77, v97
	v_fmac_f32_e32 v30, v78, v98
	v_fmac_f32_e32 v30, v79, v99
	v_fmac_f32_e32 v30, v80, v100
	v_fmac_f32_e32 v30, v81, v101
	v_fmac_f32_e32 v30, v82, v102
	v_fmac_f32_e32 v30, v83, v103
	ds_read_b128 v[96:99], v95 offset:0
	ds_read_b128 v[100:103], v95 offset:16
	s_waitcnt lgkmcnt(6)
	v_fmac_f32_e32 v31, v76, v104
	v_fmac_f32_e32 v31, v77, v105
	v_fmac_f32_e32 v31, v78, v106
	v_fmac_f32_e32 v31, v79, v107
	v_fmac_f32_e32 v31, v80, v108
	v_fmac_f32_e32 v31, v81, v109
	v_fmac_f32_e32 v31, v82, v110
	v_fmac_f32_e32 v31, v83, v111
	ds_read_b128 v[104:107], v95 offset:4096
	ds_read_b128 v[108:111], v95 offset:4112
	s_waitcnt lgkmcnt(6)
	v_fmac_f32_e32 v32, v76, v112
	v_fmac_f32_e32 v32, v77, v113
	v_fmac_f32_e32 v32, v78, v114
	v_fmac_f32_e32 v32, v79, v115
	v_fmac_f32_e32 v32, v80, v116
	v_fmac_f32_e32 v32, v81, v117
	v_fmac_f32_e32 v32, v82, v118
	v_fmac_f32_e32 v32, v83, v119
	ds_read_b128 v[112:115], v95 offset:8192
	ds_read_b128 v[116:119], v95 offset:8208
	s_waitcnt lgkmcnt(6)
	v_fmac_f32_e32 v33, v76, v120
	v_fmac_f32_e32 v33, v77, v121
	v_fmac_f32_e32 v33, v78, v122
	v_fmac_f32_e32 v33, v79, v123
	v_fmac_f32_e32 v33, v80, v124
	v_fmac_f32_e32 v33, v81, v125
	v_fmac_f32_e32 v33, v82, v126
	v_fmac_f32_e32 v33, v83, v127
	ds_read_b128 v[120:123], v95 offset:12288
	ds_read_b128 v[124:127], v95 offset:12304
	s_waitcnt lgkmcnt(6)
	v_fmac_f32_e32 v52, v76, v96
	v_fmac_f32_e32 v52, v77, v97
	v_fmac_f32_e32 v52, v78, v98
	v_fmac_f32_e32 v52, v79, v99
	v_fmac_f32_e32 v52, v80, v100
	v_fmac_f32_e32 v52, v81, v101
	v_fmac_f32_e32 v52, v82, v102
	v_fmac_f32_e32 v52, v83, v103
	ds_read_b128 v[96:99], v95 offset:16384
	ds_read_b128 v[100:103], v95 offset:16400
	s_waitcnt lgkmcnt(6)
	v_fmac_f32_e32 v53, v76, v104
	v_fmac_f32_e32 v53, v77, v105
	v_fmac_f32_e32 v53, v78, v106
	v_fmac_f32_e32 v53, v79, v107
	v_fmac_f32_e32 v53, v80, v108
	v_fmac_f32_e32 v53, v81, v109
	v_fmac_f32_e32 v53, v82, v110
	v_fmac_f32_e32 v53, v83, v111
	ds_read_b128 v[104:107], v95 offset:20480
	ds_read_b128 v[108:111], v95 offset:20496
	s_waitcnt lgkmcnt(6)
; #define LAS __attribute__((address_space(3)))
; __device__ __forceinline__ void p0_phase(LAS unsigned char* lds, const float* c, const float* w_ada, const float* b_ada, const float* w_in, const float* w_out,
;                                          float* mod, bf16* win_t, bf16* wout_t, int tid, int wid, int lane) {
;     ...
;         for (int k = 0; k < 128; k += 4) {
;             const float w0 = wp[(size_t)k * 3072], w1 = wp[(size_t)(k + 1) * 3072], w2 = wp[(size_t)(k + 2) * 3072], w3 = wp[(size_t)(k + 3) * 3072];
; #pragma unroll
;             for (int b = 0; b < 32; ++b) { const f32x4 cv = *(const LAS f32x4*)(cs + b * 1024 + kbase + k); acc[b] += cv[0] * w0 + cv[1] * w1 + cv[2] * w2 + cv[3] * w3; }
;         }
	v_fmac_f32_e32 v54, v76, v112
	v_fmac_f32_e32 v54, v77, v113
	v_fmac_f32_e32 v54, v78, v114
	v_fmac_f32_e32 v54, v79, v115
	v_fmac_f32_e32 v54, v80, v116
	v_fmac_f32_e32 v54, v81, v117
	v_fmac_f32_e32 v54, v82, v118
	v_fmac_f32_e32 v54, v83, v119
	ds_read_b128 v[112:115], v95 offset:24576
	ds_read_b128 v[116:119], v95 offset:24592
	s_waitcnt lgkmcnt(6)
	v_fmac_f32_e32 v55, v76, v120
	v_fmac_f32_e32 v55, v77, v121
	v_fmac_f32_e32 v55, v78, v122
	v_fmac_f32_e32 v55, v79, v123
	v_fmac_f32_e32 v55, v80, v124
	v_fmac_f32_e32 v55, v81, v125
	v_fmac_f32_e32 v55, v82, v126
	v_fmac_f32_e32 v55, v83, v127
	ds_read_b128 v[120:123], v95 offset:28672
	ds_read_b128 v[124:127], v95 offset:28688
	s_waitcnt lgkmcnt(6)
	v_fmac_f32_e32 v56, v76, v96
	v_fmac_f32_e32 v56, v77, v97
	v_fmac_f32_e32 v56, v78, v98
	v_fmac_f32_e32 v56, v79, v99
	v_fmac_f32_e32 v56, v80, v100
	v_fmac_f32_e32 v56, v81, v101
	v_fmac_f32_e32 v56, v82, v102
	v_fmac_f32_e32 v56, v83, v103
	ds_read_b128 v[96:99], v95 offset:32768
	ds_read_b128 v[100:103], v95 offset:32784
	s_waitcnt lgkmcnt(6)
	v_fmac_f32_e32 v57, v76, v104
	v_fmac_f32_e32 v57, v77, v105
	v_fmac_f32_e32 v57, v78, v106
	v_fmac_f32_e32 v57, v79, v107
	v_fmac_f32_e32 v57, v80, v108
	v_fmac_f32_e32 v57, v81, v109
	v_fmac_f32_e32 v57, v82, v110
	v_fmac_f32_e32 v57, v83, v111
	ds_read_b128 v[104:107], v95 offset:36864
	ds_read_b128 v[108:111], v95 offset:36880
	s_waitcnt lgkmcnt(6)
	v_fmac_f32_e32 v50, v76, v112
	v_fmac_f32_e32 v50, v77, v113
	v_fmac_f32_e32 v50, v78, v114
	v_fmac_f32_e32 v50, v79, v115
	v_fmac_f32_e32 v50, v80, v116
	v_fmac_f32_e32 v50, v81, v117
	v_fmac_f32_e32 v50, v82, v118
	v_fmac_f32_e32 v50, v83, v119
	ds_read_b128 v[112:115], v95 offset:40960
	ds_read_b128 v[116:119], v95 offset:40976
	s_waitcnt lgkmcnt(6)
	v_fmac_f32_e32 v51, v76, v120
	v_fmac_f32_e32 v51, v77, v121
	v_fmac_f32_e32 v51, v78, v122
	v_fmac_f32_e32 v51, v79, v123
	v_fmac_f32_e32 v51, v80, v124
	v_fmac_f32_e32 v51, v81, v125
	v_fmac_f32_e32 v51, v82, v126
	v_fmac_f32_e32 v51, v83, v127
	ds_read_b128 v[120:123], v95 offset:45056
	ds_read_b128 v[124:127], v95 offset:45072
	s_waitcnt lgkmcnt(6)
	v_fmac_f32_e32 v48, v76, v96
	v_fmac_f32_e32 v48, v77, v97
	v_fmac_f32_e32 v48, v78, v98
	v_fmac_f32_e32 v48, v79, v99
	v_fmac_f32_e32 v48, v80, v100
	v_fmac_f32_e32 v48, v81, v101
	v_fmac_f32_e32 v48, v82, v102
	v_fmac_f32_e32 v48, v83, v103
	ds_read_b128 v[96:99], v95 offset:49152
	ds_read_b128 v[100:103], v95 offset:49168
	s_waitcnt lgkmcnt(6)
	v_fmac_f32_e32 v49, v76, v104
	v_fmac_f32_e32 v49, v77, v105
	v_fmac_f32_e32 v49, v78, v106
	v_fmac_f32_e32 v49, v79, v107
	v_fmac_f32_e32 v49, v80, v108
	v_fmac_f32_e32 v49, v81, v109
	v_fmac_f32_e32 v49, v82, v110
	v_fmac_f32_e32 v49, v83, v111
	ds_read_b128 v[104:107], v95 offset:53248
	ds_read_b128 v[108:111], v95 offset:53264
	s_waitcnt lgkmcnt(6)
	v_fmac_f32_e32 v46, v76, v112
	v_fmac_f32_e32 v46, v77, v113
	v_fmac_f32_e32 v46, v78, v114
	v_fmac_f32_e32 v46, v79, v115
	v_fmac_f32_e32 v46, v80, v116
	v_fmac_f32_e32 v46, v81, v117
	v_fmac_f32_e32 v46, v82, v118
	v_fmac_f32_e32 v46, v83, v119
	ds_read_b128 v[112:115], v95 offset:57344
	ds_read_b128 v[116:119], v95 offset:57360
	s_waitcnt lgkmcnt(6)
	v_fmac_f32_e32 v47, v76, v120
	v_fmac_f32_e32 v47, v77, v121
	v_fmac_f32_e32 v47, v78, v122
	v_fmac_f32_e32 v47, v79, v123
	v_fmac_f32_e32 v47, v80, v124
	v_fmac_f32_e32 v47, v81, v125
	v_fmac_f32_e32 v47, v82, v126
	v_fmac_f32_e32 v47, v83, v127
	ds_read_b128 v[120:123], v95 offset:61440
	ds_read_b128 v[124:127], v95 offset:61456
	s_waitcnt lgkmcnt(6)
	v_fmac_f32_e32 v44, v76, v96
	v_fmac_f32_e32 v44, v77, v97
	v_fmac_f32_e32 v44, v78, v98
	v_fmac_f32_e32 v44, v79, v99
	v_fmac_f32_e32 v44, v80, v100
	v_fmac_f32_e32 v44, v81, v101
	v_fmac_f32_e32 v44, v82, v102
	v_fmac_f32_e32 v44, v83, v103
	s_waitcnt lgkmcnt(4)
	v_fmac_f32_e32 v45, v76, v104
	v_fmac_f32_e32 v45, v77, v105
	v_fmac_f32_e32 v45, v78, v106
	v_fmac_f32_e32 v45, v79, v107
	v_fmac_f32_e32 v45, v80, v108
	v_fmac_f32_e32 v45, v81, v109
	v_fmac_f32_e32 v45, v82, v110
	v_fmac_f32_e32 v45, v83, v111
	s_waitcnt lgkmcnt(2)
	v_fmac_f32_e32 v34, v76, v112
	v_fmac_f32_e32 v34, v77, v113
	v_fmac_f32_e32 v34, v78, v114
	v_fmac_f32_e32 v34, v79, v115
	v_fmac_f32_e32 v34, v80, v116
	v_fmac_f32_e32 v34, v81, v117
	v_fmac_f32_e32 v34, v82, v118
	v_fmac_f32_e32 v34, v83, v119
	s_waitcnt lgkmcnt(0)
	v_fmac_f32_e32 v35, v76, v120
	v_fmac_f32_e32 v35, v77, v121
	v_fmac_f32_e32 v35, v78, v122
	v_fmac_f32_e32 v35, v79, v123
	v_fmac_f32_e32 v35, v80, v124
	v_fmac_f32_e32 v35, v81, v125
	v_fmac_f32_e32 v35, v82, v126
	v_fmac_f32_e32 v35, v83, v127
	s_cmp_eq_u32 s52, 1
	s_cselect_b32 s50, 0xfffe8000, 0
	s_cselect_b32 s51, -1, 0
	v_lshl_add_u64 v[16:17], v[16:17], 0, s[50:51]
	v_add_co_u32_e32 v92, vcc, s24, v16
	s_nop 1
	v_addc_co_u32_e32 v93, vcc, -1, v17, vcc
	global_load_dword v76, v[92:93], off
	v_lshl_add_u64 v[92:93], v[92:93], 0, s[48:49]
	global_load_dword v77, v[92:93], off
	v_lshl_add_u64 v[92:93], v[92:93], 0, s[48:49]
	global_load_dword v78, v[92:93], off
	v_lshl_add_u64 v[92:93], v[92:93], 0, s[48:49]
	global_load_dword v79, v[92:93], off
	v_lshl_add_u64 v[92:93], v[92:93], 0, s[48:49]
	global_load_dword v80, v[92:93], off
	v_lshl_add_u64 v[92:93], v[92:93], 0, s[48:49]
	global_load_dword v81, v[92:93], off
	v_lshl_add_u64 v[92:93], v[92:93], 0, s[48:49]
	global_load_dword v82, v[92:93], off
	v_lshl_add_u64 v[92:93], v[92:93], 0, s[48:49]
	global_load_dword v83, v[92:93], off
	v_lshl_add_u64 v[16:17], v[16:17], 0, s[14:15]
	s_waitcnt vmcnt(8)
; #define LAS __attribute__((address_space(3)))
; __device__ __forceinline__ void p0_phase(LAS unsigned char* lds, const float* c, const float* w_ada, const float* b_ada, const float* w_in, const float* w_out,
;                                          float* mod, bf16* win_t, bf16* wout_t, int tid, int wid, int lane) {
;     ...
;         for (int k = 0; k < 128; k += 4) {
;             const float w0 = wp[(size_t)k * 3072], w1 = wp[(size_t)(k + 1) * 3072], w2 = wp[(size_t)(k + 2) * 3072], w3 = wp[(size_t)(k + 3) * 3072];
; #pragma unroll
;             for (int b = 0; b < 32; ++b) { const f32x4 cv = *(const LAS f32x4*)(cs + b * 1024 + kbase + k); acc[b] += cv[0] * w0 + cv[1] * w1 + cv[2] * w2 + cv[3] * w3; }
;         }
	ds_read_b128 v[96:99], v94 offset:32
	ds_read_b128 v[100:103], v94 offset:48
	ds_read_b128 v[104:107], v94 offset:4128
	ds_read_b128 v[108:111], v94 offset:4144
	ds_read_b128 v[112:115], v94 offset:8224
	ds_read_b128 v[116:119], v94 offset:8240
	ds_read_b128 v[120:123], v94 offset:12320
	ds_read_b128 v[124:127], v94 offset:12336
	s_waitcnt lgkmcnt(6)
	v_fmac_f32_e32 v18, v84, v96
	v_fmac_f32_e32 v18, v85, v97
	v_fmac_f32_e32 v18, v86, v98
	v_fmac_f32_e32 v18, v87, v99
	v_fmac_f32_e32 v18, v88, v100
	v_fmac_f32_e32 v18, v89, v101
	v_fmac_f32_e32 v18, v90, v102
	v_fmac_f32_e32 v18, v91, v103
	ds_read_b128 v[96:99], v94 offset:16416
	ds_read_b128 v[100:103], v94 offset:16432
	s_waitcnt lgkmcnt(6)
	v_fmac_f32_e32 v19, v84, v104
	v_fmac_f32_e32 v19, v85, v105
	v_fmac_f32_e32 v19, v86, v106
	v_fmac_f32_e32 v19, v87, v107
	v_fmac_f32_e32 v19, v88, v108
	v_fmac_f32_e32 v19, v89, v109
	v_fmac_f32_e32 v19, v90, v110
	v_fmac_f32_e32 v19, v91, v111
	ds_read_b128 v[104:107], v94 offset:20512
	ds_read_b128 v[108:111], v94 offset:20528
	s_waitcnt lgkmcnt(6)
	v_fmac_f32_e32 v20, v84, v112
	v_fmac_f32_e32 v20, v85, v113
	v_fmac_f32_e32 v20, v86, v114
	v_fmac_f32_e32 v20, v87, v115
	v_fmac_f32_e32 v20, v88, v116
	v_fmac_f32_e32 v20, v89, v117
	v_fmac_f32_e32 v20, v90, v118
	v_fmac_f32_e32 v20, v91, v119
	ds_read_b128 v[112:115], v94 offset:24608
	ds_read_b128 v[116:119], v94 offset:24624
	s_waitcnt lgkmcnt(6)
	v_fmac_f32_e32 v21, v84, v120
	v_fmac_f32_e32 v21, v85, v121
	v_fmac_f32_e32 v21, v86, v122
	v_fmac_f32_e32 v21, v87, v123
	v_fmac_f32_e32 v21, v88, v124
	v_fmac_f32_e32 v21, v89, v125
	v_fmac_f32_e32 v21, v90, v126
	v_fmac_f32_e32 v21, v91, v127
	ds_read_b128 v[120:123], v94 offset:28704
	ds_read_b128 v[124:127], v94 offset:28720
	s_waitcnt lgkmcnt(6)
	v_fmac_f32_e32 v22, v84, v96
	v_fmac_f32_e32 v22, v85, v97
	v_fmac_f32_e32 v22, v86, v98
	v_fmac_f32_e32 v22, v87, v99
	v_fmac_f32_e32 v22, v88, v100
	v_fmac_f32_e32 v22, v89, v101
	v_fmac_f32_e32 v22, v90, v102
	v_fmac_f32_e32 v22, v91, v103
	ds_read_b128 v[96:99], v94 offset:32800
	ds_read_b128 v[100:103], v94 offset:32816
	s_waitcnt lgkmcnt(6)
	v_fmac_f32_e32 v23, v84, v104
	v_fmac_f32_e32 v23, v85, v105
	v_fmac_f32_e32 v23, v86, v106
	v_fmac_f32_e32 v23, v87, v107
	v_fmac_f32_e32 v23, v88, v108
	v_fmac_f32_e32 v23, v89, v109
	v_fmac_f32_e32 v23, v90, v110
	v_fmac_f32_e32 v23, v91, v111
	ds_read_b128 v[104:107], v94 offset:36896
	ds_read_b128 v[108:111], v94 offset:36912
	s_waitcnt lgkmcnt(6)
	v_fmac_f32_e32 v24, v84, v112
	v_fmac_f32_e32 v24, v85, v113
	v_fmac_f32_e32 v24, v86, v114
	v_fmac_f32_e32 v24, v87, v115
	v_fmac_f32_e32 v24, v88, v116
	v_fmac_f32_e32 v24, v89, v117
	v_fmac_f32_e32 v24, v90, v118
	v_fmac_f32_e32 v24, v91, v119
	ds_read_b128 v[112:115], v94 offset:40992
	ds_read_b128 v[116:119], v94 offset:41008
	s_waitcnt lgkmcnt(6)
	v_fmac_f32_e32 v25, v84, v120
	v_fmac_f32_e32 v25, v85, v121
	v_fmac_f32_e32 v25, v86, v122
	v_fmac_f32_e32 v25, v87, v123
	v_fmac_f32_e32 v25, v88, v124
	v_fmac_f32_e32 v25, v89, v125
	v_fmac_f32_e32 v25, v90, v126
	v_fmac_f32_e32 v25, v91, v127
	ds_read_b128 v[120:123], v94 offset:45088
	ds_read_b128 v[124:127], v94 offset:45104
	s_waitcnt lgkmcnt(6)
	v_fmac_f32_e32 v26, v84, v96
	v_fmac_f32_e32 v26, v85, v97
	v_fmac_f32_e32 v26, v86, v98
	v_fmac_f32_e32 v26, v87, v99
	v_fmac_f32_e32 v26, v88, v100
	v_fmac_f32_e32 v26, v89, v101
	v_fmac_f32_e32 v26, v90, v102
	v_fmac_f32_e32 v26, v91, v103
	ds_read_b128 v[96:99], v94 offset:49184
	ds_read_b128 v[100:103], v94 offset:49200
	s_waitcnt lgkmcnt(6)
	v_fmac_f32_e32 v27, v84, v104
	v_fmac_f32_e32 v27, v85, v105
	v_fmac_f32_e32 v27, v86, v106
	v_fmac_f32_e32 v27, v87, v107
	v_fmac_f32_e32 v27, v88, v108
	v_fmac_f32_e32 v27, v89, v109
	v_fmac_f32_e32 v27, v90, v110
	v_fmac_f32_e32 v27, v91, v111
	ds_read_b128 v[104:107], v94 offset:53280
	ds_read_b128 v[108:111], v94 offset:53296
	s_waitcnt lgkmcnt(6)
	v_fmac_f32_e32 v28, v84, v112
	v_fmac_f32_e32 v28, v85, v113
	v_fmac_f32_e32 v28, v86, v114
	v_fmac_f32_e32 v28, v87, v115
	v_fmac_f32_e32 v28, v88, v116
	v_fmac_f32_e32 v28, v89, v117
	v_fmac_f32_e32 v28, v90, v118
	v_fmac_f32_e32 v28, v91, v119
	ds_read_b128 v[112:115], v94 offset:57376
	ds_read_b128 v[116:119], v94 offset:57392
	s_waitcnt lgkmcnt(6)
	v_fmac_f32_e32 v29, v84, v120
	v_fmac_f32_e32 v29, v85, v121
	v_fmac_f32_e32 v29, v86, v122
	v_fmac_f32_e32 v29, v87, v123
	v_fmac_f32_e32 v29, v88, v124
	v_fmac_f32_e32 v29, v89, v125
	v_fmac_f32_e32 v29, v90, v126
	v_fmac_f32_e32 v29, v91, v127
	ds_read_b128 v[120:123], v94 offset:61472
	ds_read_b128 v[124:127], v94 offset:61488
	s_waitcnt lgkmcnt(6)
	v_fmac_f32_e32 v30, v84, v96
	v_fmac_f32_e32 v30, v85, v97
	v_fmac_f32_e32 v30, v86, v98
	v_fmac_f32_e32 v30, v87, v99
	v_fmac_f32_e32 v30, v88, v100
	v_fmac_f32_e32 v30, v89, v101
	v_fmac_f32_e32 v30, v90, v102
	v_fmac_f32_e32 v30, v91, v103
	ds_read_b128 v[96:99], v95 offset:32
	ds_read_b128 v[100:103], v95 offset:48
	s_waitcnt lgkmcnt(6)
	v_fmac_f32_e32 v31, v84, v104
	v_fmac_f32_e32 v31, v85, v105
	v_fmac_f32_e32 v31, v86, v106
	v_fmac_f32_e32 v31, v87, v107
	v_fmac_f32_e32 v31, v88, v108
	v_fmac_f32_e32 v31, v89, v109
	v_fmac_f32_e32 v31, v90, v110
	v_fmac_f32_e32 v31, v91, v111
	ds_read_b128 v[104:107], v95 offset:4128
	ds_read_b128 v[108:111], v95 offset:4144
	s_waitcnt lgkmcnt(6)
	v_fmac_f32_e32 v32, v84, v112
	v_fmac_f32_e32 v32, v85, v113
	v_fmac_f32_e32 v32, v86, v114
	v_fmac_f32_e32 v32, v87, v115
	v_fmac_f32_e32 v32, v88, v116
	v_fmac_f32_e32 v32, v89, v117
	v_fmac_f32_e32 v32, v90, v118
	v_fmac_f32_e32 v32, v91, v119
	ds_read_b128 v[112:115], v95 offset:8224
	ds_read_b128 v[116:119], v95 offset:8240
	s_waitcnt lgkmcnt(6)
; #define LAS __attribute__((address_space(3)))
; __device__ __forceinline__ void p0_phase(LAS unsigned char* lds, const float* c, const float* w_ada, const float* b_ada, const float* w_in, const float* w_out,
;                                          float* mod, bf16* win_t, bf16* wout_t, int tid, int wid, int lane) {
;     ...
;         for (int k = 0; k < 128; k += 4) {
;             const float w0 = wp[(size_t)k * 3072], w1 = wp[(size_t)(k + 1) * 3072], w2 = wp[(size_t)(k + 2) * 3072], w3 = wp[(size_t)(k + 3) * 3072];
; #pragma unroll
;             for (int b = 0; b < 32; ++b) { const f32x4 cv = *(const LAS f32x4*)(cs + b * 1024 + kbase + k); acc[b] += cv[0] * w0 + cv[1] * w1 + cv[2] * w2 + cv[3] * w3; }
;         }
	v_fmac_f32_e32 v33, v84, v120
	v_fmac_f32_e32 v33, v85, v121
	v_fmac_f32_e32 v33, v86, v122
	v_fmac_f32_e32 v33, v87, v123
	v_fmac_f32_e32 v33, v88, v124
	v_fmac_f32_e32 v33, v89, v125
	v_fmac_f32_e32 v33, v90, v126
	v_fmac_f32_e32 v33, v91, v127
	ds_read_b128 v[120:123], v95 offset:12320
	ds_read_b128 v[124:127], v95 offset:12336
	s_waitcnt lgkmcnt(6)
	v_fmac_f32_e32 v52, v84, v96
	v_fmac_f32_e32 v52, v85, v97
	v_fmac_f32_e32 v52, v86, v98
	v_fmac_f32_e32 v52, v87, v99
	v_fmac_f32_e32 v52, v88, v100
	v_fmac_f32_e32 v52, v89, v101
	v_fmac_f32_e32 v52, v90, v102
	v_fmac_f32_e32 v52, v91, v103
	ds_read_b128 v[96:99], v95 offset:16416
	ds_read_b128 v[100:103], v95 offset:16432
	s_waitcnt lgkmcnt(6)
	v_fmac_f32_e32 v53, v84, v104
	v_fmac_f32_e32 v53, v85, v105
	v_fmac_f32_e32 v53, v86, v106
	v_fmac_f32_e32 v53, v87, v107
	v_fmac_f32_e32 v53, v88, v108
	v_fmac_f32_e32 v53, v89, v109
	v_fmac_f32_e32 v53, v90, v110
	v_fmac_f32_e32 v53, v91, v111
	ds_read_b128 v[104:107], v95 offset:20512
	ds_read_b128 v[108:111], v95 offset:20528
	s_waitcnt lgkmcnt(6)
	v_fmac_f32_e32 v54, v84, v112
	v_fmac_f32_e32 v54, v85, v113
	v_fmac_f32_e32 v54, v86, v114
	v_fmac_f32_e32 v54, v87, v115
	v_fmac_f32_e32 v54, v88, v116
	v_fmac_f32_e32 v54, v89, v117
	v_fmac_f32_e32 v54, v90, v118
	v_fmac_f32_e32 v54, v91, v119
	ds_read_b128 v[112:115], v95 offset:24608
	ds_read_b128 v[116:119], v95 offset:24624
	s_waitcnt lgkmcnt(6)
	v_fmac_f32_e32 v55, v84, v120
	v_fmac_f32_e32 v55, v85, v121
	v_fmac_f32_e32 v55, v86, v122
	v_fmac_f32_e32 v55, v87, v123
	v_fmac_f32_e32 v55, v88, v124
	v_fmac_f32_e32 v55, v89, v125
	v_fmac_f32_e32 v55, v90, v126
	v_fmac_f32_e32 v55, v91, v127
	ds_read_b128 v[120:123], v95 offset:28704
	ds_read_b128 v[124:127], v95 offset:28720
	s_waitcnt lgkmcnt(6)
	v_fmac_f32_e32 v56, v84, v96
	v_fmac_f32_e32 v56, v85, v97
	v_fmac_f32_e32 v56, v86, v98
	v_fmac_f32_e32 v56, v87, v99
	v_fmac_f32_e32 v56, v88, v100
	v_fmac_f32_e32 v56, v89, v101
	v_fmac_f32_e32 v56, v90, v102
	v_fmac_f32_e32 v56, v91, v103
	ds_read_b128 v[96:99], v95 offset:32800
	ds_read_b128 v[100:103], v95 offset:32816
	s_waitcnt lgkmcnt(6)
	v_fmac_f32_e32 v57, v84, v104
	v_fmac_f32_e32 v57, v85, v105
	v_fmac_f32_e32 v57, v86, v106
	v_fmac_f32_e32 v57, v87, v107
	v_fmac_f32_e32 v57, v88, v108
	v_fmac_f32_e32 v57, v89, v109
	v_fmac_f32_e32 v57, v90, v110
	v_fmac_f32_e32 v57, v91, v111
	ds_read_b128 v[104:107], v95 offset:36896
	ds_read_b128 v[108:111], v95 offset:36912
	s_waitcnt lgkmcnt(6)
	v_fmac_f32_e32 v50, v84, v112
	v_fmac_f32_e32 v50, v85, v113
	v_fmac_f32_e32 v50, v86, v114
	v_fmac_f32_e32 v50, v87, v115
	v_fmac_f32_e32 v50, v88, v116
	v_fmac_f32_e32 v50, v89, v117
	v_fmac_f32_e32 v50, v90, v118
	v_fmac_f32_e32 v50, v91, v119
	ds_read_b128 v[112:115], v95 offset:40992
	ds_read_b128 v[116:119], v95 offset:41008
	s_waitcnt lgkmcnt(6)
	v_fmac_f32_e32 v51, v84, v120
	v_fmac_f32_e32 v51, v85, v121
	v_fmac_f32_e32 v51, v86, v122
	v_fmac_f32_e32 v51, v87, v123
	v_fmac_f32_e32 v51, v88, v124
	v_fmac_f32_e32 v51, v89, v125
	v_fmac_f32_e32 v51, v90, v126
	v_fmac_f32_e32 v51, v91, v127
	ds_read_b128 v[120:123], v95 offset:45088
	ds_read_b128 v[124:127], v95 offset:45104
	s_waitcnt lgkmcnt(6)
	v_fmac_f32_e32 v48, v84, v96
	v_fmac_f32_e32 v48, v85, v97
	v_fmac_f32_e32 v48, v86, v98
	v_fmac_f32_e32 v48, v87, v99
	v_fmac_f32_e32 v48, v88, v100
	v_fmac_f32_e32 v48, v89, v101
	v_fmac_f32_e32 v48, v90, v102
	v_fmac_f32_e32 v48, v91, v103
	ds_read_b128 v[96:99], v95 offset:49184
	ds_read_b128 v[100:103], v95 offset:49200
	s_waitcnt lgkmcnt(6)
	v_fmac_f32_e32 v49, v84, v104
	v_fmac_f32_e32 v49, v85, v105
	v_fmac_f32_e32 v49, v86, v106
	v_fmac_f32_e32 v49, v87, v107
	v_fmac_f32_e32 v49, v88, v108
	v_fmac_f32_e32 v49, v89, v109
	v_fmac_f32_e32 v49, v90, v110
	v_fmac_f32_e32 v49, v91, v111
	ds_read_b128 v[104:107], v95 offset:53280
	ds_read_b128 v[108:111], v95 offset:53296
	s_waitcnt lgkmcnt(6)
	v_fmac_f32_e32 v46, v84, v112
	v_fmac_f32_e32 v46, v85, v113
	v_fmac_f32_e32 v46, v86, v114
	v_fmac_f32_e32 v46, v87, v115
	v_fmac_f32_e32 v46, v88, v116
	v_fmac_f32_e32 v46, v89, v117
	v_fmac_f32_e32 v46, v90, v118
	v_fmac_f32_e32 v46, v91, v119
	ds_read_b128 v[112:115], v95 offset:57376
	ds_read_b128 v[116:119], v95 offset:57392
	s_waitcnt lgkmcnt(6)
	v_fmac_f32_e32 v47, v84, v120
	v_fmac_f32_e32 v47, v85, v121
	v_fmac_f32_e32 v47, v86, v122
	v_fmac_f32_e32 v47, v87, v123
	v_fmac_f32_e32 v47, v88, v124
	v_fmac_f32_e32 v47, v89, v125
	v_fmac_f32_e32 v47, v90, v126
	v_fmac_f32_e32 v47, v91, v127
	ds_read_b128 v[120:123], v95 offset:61472
	ds_read_b128 v[124:127], v95 offset:61488
	s_waitcnt lgkmcnt(6)
	v_fmac_f32_e32 v44, v84, v96
	v_fmac_f32_e32 v44, v85, v97
	v_fmac_f32_e32 v44, v86, v98
	v_fmac_f32_e32 v44, v87, v99
	v_fmac_f32_e32 v44, v88, v100
	v_fmac_f32_e32 v44, v89, v101
	v_fmac_f32_e32 v44, v90, v102
	v_fmac_f32_e32 v44, v91, v103
	s_waitcnt lgkmcnt(4)
	v_fmac_f32_e32 v45, v84, v104
	v_fmac_f32_e32 v45, v85, v105
	v_fmac_f32_e32 v45, v86, v106
	v_fmac_f32_e32 v45, v87, v107
	v_fmac_f32_e32 v45, v88, v108
	v_fmac_f32_e32 v45, v89, v109
	v_fmac_f32_e32 v45, v90, v110
	v_fmac_f32_e32 v45, v91, v111
	s_waitcnt lgkmcnt(2)
	v_fmac_f32_e32 v34, v84, v112
	v_fmac_f32_e32 v34, v85, v113
	v_fmac_f32_e32 v34, v86, v114
	v_fmac_f32_e32 v34, v87, v115
	v_fmac_f32_e32 v34, v88, v116
	v_fmac_f32_e32 v34, v89, v117
	v_fmac_f32_e32 v34, v90, v118
	v_fmac_f32_e32 v34, v91, v119
	s_waitcnt lgkmcnt(0)
	v_fmac_f32_e32 v35, v84, v120
	v_fmac_f32_e32 v35, v85, v121
	v_fmac_f32_e32 v35, v86, v122
	v_fmac_f32_e32 v35, v87, v123
	v_fmac_f32_e32 v35, v88, v124
	v_fmac_f32_e32 v35, v89, v125
	v_fmac_f32_e32 v35, v90, v126
	v_fmac_f32_e32 v35, v91, v127
	s_add_i32 s35, s35, 64
	s_add_i32 s52, s52, -1
	s_cmp_eq_u32 s52, 0
	s_cbranch_scc0 .LBB0_21
; #define LAS __attribute__((address_space(3)))
; __device__ __forceinline__ void p0_phase(LAS unsigned char* lds, const float* c, const float* w_ada, const float* b_ada, const float* w_in, const float* w_out,
;                                          float* mod, bf16* win_t, bf16* wout_t, int tid, int wid, int lane) {
;     ...
;         __syncthreads();
;         LAS float* part = (LAS float*)lds;
; #pragma unroll
;         for (int b = 0; b < 32; ++b) part[(wid * 32 + b) * 64 + lane] = acc[b];
;         __syncthreads();
;         {
;             const int nn = tid & 63, bg = tid >> 6;
; #pragma unroll
;             for (int bb = 0; bb < 4; ++bb) { const int b = bg * 4 + bb; float s = 0.f;
; #pragma unroll
;                 for (int w = 0; w < 8; ++w) s += part[(w * 32 + b) * 64 + nn];
;                 mod[((size_t)l * 32 + b) * 3072 + nb * 64 + nn] = s + b_ada[l * 3072 + nb * 64 + nn]; }
;         }
	s_waitcnt vmcnt(0)
	s_mul_i32 s34, s16, 48
	s_sub_i32 s34, s31, s34
	s_lshl_b32 s34, s34, 6
	v_add_u32_e32 v0, s19, v39
	s_add_i32 s33, s33, s34
	s_barrier
	ds_write2st64_b32 v0, v18, v19 offset1:1
	ds_write2st64_b32 v0, v20, v21 offset0:2 offset1:3
	ds_write2st64_b32 v0, v22, v23 offset0:4 offset1:5
	ds_write2st64_b32 v0, v24, v25 offset0:6 offset1:7
	ds_write2st64_b32 v0, v26, v27 offset0:8 offset1:9
	ds_write2st64_b32 v0, v28, v29 offset0:10 offset1:11
	ds_write2st64_b32 v0, v30, v31 offset0:12 offset1:13
	ds_write2st64_b32 v0, v32, v33 offset0:14 offset1:15
	ds_write2st64_b32 v0, v52, v53 offset0:16 offset1:17
	ds_write2st64_b32 v0, v54, v55 offset0:18 offset1:19
	ds_write2st64_b32 v0, v56, v57 offset0:20 offset1:21
	ds_write2st64_b32 v0, v50, v51 offset0:22 offset1:23
	ds_write2st64_b32 v0, v48, v49 offset0:24 offset1:25
	ds_write2st64_b32 v0, v46, v47 offset0:26 offset1:27
	ds_write2st64_b32 v0, v44, v45 offset0:28 offset1:29
	ds_write2st64_b32 v0, v34, v35 offset0:30 offset1:31
	v_or_b32_e32 v0, s33, v203
	v_ashrrev_i32_e32 v1, 31, v0
	v_lshl_add_u64 v[0:1], v[0:1], 2, s[4:5]
	s_waitcnt lgkmcnt(0)
	s_barrier
	global_load_dword v28, v[0:1], off
	ds_read2st64_b32 v[2:3], v59 offset1:32
	ds_read2st64_b32 v[16:17], v59 offset0:64 offset1:96
	ds_read2st64_b32 v[18:19], v59 offset0:128 offset1:160
	ds_read2st64_b32 v[20:21], v59 offset0:192 offset1:224
	s_lshl_b64 s[16:17], s[16:17], 5
	s_waitcnt lgkmcnt(3)
	v_add_f32_e32 v2, 0, v2
	v_add_f32_e32 v2, v2, v3
	s_waitcnt lgkmcnt(2)
	v_add_f32_e32 v2, v2, v16
	v_add_f32_e32 v2, v2, v17
	s_waitcnt lgkmcnt(1)
	v_add_f32_e32 v2, v2, v18
	s_ashr_i32 s35, s34, 31
	v_add_f32_e32 v2, v2, v19
	v_lshl_add_u64 v[22:23], s[16:17], 0, v[6:7]
	v_lshl_add_u64 v[24:25], s[34:35], 2, v[8:9]
	s_waitcnt lgkmcnt(0)
	v_add_f32_e32 v2, v2, v20
	v_mad_u64_u32 v[26:27], s[34:35], v22, s3, v[24:25]
	v_add_f32_e32 v2, v2, v21
	v_mad_i32_i24 v27, v23, s3, v27
	v_lshl_add_u64 v[22:23], s[16:17], 0, v[4:5]
	s_add_i32 s31, s31, s20
	s_cmpk_gt_i32 s31, 0x5f
	s_waitcnt vmcnt(0)
	v_add_f32_e32 v2, v2, v28
	global_store_dword v[26:27], v2, off
	global_load_dword v28, v[0:1], off
	ds_read2st64_b32 v[2:3], v60 offset1:32
	ds_read2st64_b32 v[16:17], v60 offset0:64 offset1:96
	ds_read2st64_b32 v[18:19], v60 offset0:128 offset1:160
	ds_read2st64_b32 v[20:21], v60 offset0:192 offset1:224
	v_mad_u64_u32 v[26:27], s[34:35], v22, s3, v[24:25]
	s_waitcnt lgkmcnt(3)
	v_add_f32_e32 v2, 0, v2
	v_add_f32_e32 v2, v2, v3
	s_waitcnt lgkmcnt(2)
	v_add_f32_e32 v2, v2, v16
	v_add_f32_e32 v2, v2, v17
	s_waitcnt lgkmcnt(1)
	v_add_f32_e32 v2, v2, v18
	v_add_f32_e32 v2, v2, v19
	s_waitcnt lgkmcnt(0)
	v_add_f32_e32 v2, v2, v20
	v_add_f32_e32 v2, v2, v21
	v_mad_i32_i24 v27, v23, s3, v27
	v_lshl_add_u64 v[22:23], s[16:17], 0, v[10:11]
	s_waitcnt vmcnt(0)
	v_add_f32_e32 v2, v2, v28
	global_store_dword v[26:27], v2, off
	global_load_dword v28, v[0:1], off
	ds_read2st64_b32 v[2:3], v61 offset1:32
	ds_read2st64_b32 v[16:17], v61 offset0:64 offset1:96
	ds_read2st64_b32 v[18:19], v61 offset0:128 offset1:160
	ds_read2st64_b32 v[20:21], v61 offset0:192 offset1:224
	v_mad_u64_u32 v[26:27], s[34:35], v22, s3, v[24:25]
	s_waitcnt lgkmcnt(3)
	v_add_f32_e32 v2, 0, v2
	v_add_f32_e32 v2, v2, v3
	s_waitcnt lgkmcnt(2)
	v_add_f32_e32 v2, v2, v16
	v_add_f32_e32 v2, v2, v17
	s_waitcnt lgkmcnt(1)
	v_add_f32_e32 v2, v2, v18
	v_add_f32_e32 v2, v2, v19
	s_waitcnt lgkmcnt(0)
	v_add_f32_e32 v2, v2, v20
	v_add_f32_e32 v2, v2, v21
	v_mad_i32_i24 v27, v23, s3, v27
	v_lshl_add_u64 v[20:21], s[16:17], 0, v[12:13]
	v_mad_u64_u32 v[22:23], s[16:17], v20, s3, v[24:25]
	v_mad_i32_i24 v23, v21, s3, v23
	s_waitcnt vmcnt(0)
	v_add_f32_e32 v2, v2, v28
	global_store_dword v[26:27], v2, off
	global_load_dword v26, v[0:1], off
	ds_read2st64_b32 v[0:1], v62 offset1:32
	ds_read2st64_b32 v[2:3], v62 offset0:64 offset1:96
	ds_read2st64_b32 v[16:17], v62 offset0:128 offset1:160
	ds_read2st64_b32 v[18:19], v62 offset0:192 offset1:224
	s_waitcnt lgkmcnt(3)
	v_add_f32_e32 v0, 0, v0
	v_add_f32_e32 v0, v0, v1
	s_waitcnt lgkmcnt(2)
	v_add_f32_e32 v0, v0, v2
	v_add_f32_e32 v0, v0, v3
	s_waitcnt lgkmcnt(1)
	v_add_f32_e32 v0, v0, v16
	v_add_f32_e32 v0, v0, v17
	s_waitcnt lgkmcnt(0)
	v_add_f32_e32 v0, v0, v18
	v_add_f32_e32 v0, v0, v19
	s_waitcnt vmcnt(0)
	v_add_f32_e32 v0, v0, v26
	global_store_dword v[22:23], v0, off
	s_cbranch_scc0 .LBB0_18

; template <bool WIN>
; __device__ __forceinline__ void p0_transpose_item(const float* W, int srcN, bf16* WT, LAS float* scr, int item, int nblk, int lane) {
;     ...
;     const int nd = n0 + (lane & 31);
;     int sc = nd;
;     if (WIN) { sc = nd < PSQ ? nd : (nd < PGI ? nd + 8 : (nd < DIN ? nd - PGI + 2688 : -1)); }
; #pragma unroll 8
;     for (int i = 0; i < 32; ++i) { const int kk = 2 * i + (lane >> 5); scr[kk * 33 + (lane & 31)] = sc >= 0 ? W[(size_t)(k0 + kk) * srcN + sc] : 0.f; }
.LBB0_44:
	v_mov_b32_e32 v100, 0
	v_mov_b32_e32 v101, 0
	v_mov_b32_e32 v102, 0
	v_mov_b32_e32 v103, 0
	v_mov_b32_e32 v104, 0
	v_mov_b32_e32 v105, 0
	v_mov_b32_e32 v106, 0
	v_mov_b32_e32 v107, 0
	v_mov_b32_e32 v108, 0
	v_mov_b32_e32 v109, 0
	v_mov_b32_e32 v110, 0
	v_mov_b32_e32 v111, 0
	v_mov_b32_e32 v112, 0
	v_mov_b32_e32 v113, 0
	v_mov_b32_e32 v114, 0
	v_mov_b32_e32 v115, 0
	v_mov_b32_e32 v116, 0
	v_mov_b32_e32 v117, 0
	v_mov_b32_e32 v118, 0
	v_mov_b32_e32 v119, 0
	v_mov_b32_e32 v120, 0
	v_mov_b32_e32 v121, 0
	v_mov_b32_e32 v122, 0
	v_mov_b32_e32 v123, 0
	v_mov_b32_e32 v124, 0
	v_mov_b32_e32 v125, 0
	v_mov_b32_e32 v126, 0
	v_mov_b32_e32 v127, 0
	v_mov_b32_e32 v128, 0
	v_mov_b32_e32 v129, 0
	v_mov_b32_e32 v130, 0
	v_mov_b32_e32 v131, 0
	s_and_saveexec_b64 s[12:13], vcc
	s_cbranch_execz .Lp0win_skip
	v_lshl_add_u64 v[40:41], v[22:23], 0, s[10:11]
	global_load_dword v100, v[40:41], off
	v_lshl_add_u64 v[40:41], v[20:21], 0, s[10:11]
	global_load_dword v101, v[40:41], off
	v_lshl_add_u64 v[40:41], v[18:19], 0, s[10:11]
	global_load_dword v102, v[40:41], off
	v_lshl_add_u64 v[40:41], v[16:17], 0, s[10:11]
	global_load_dword v103, v[40:41], off
	v_lshl_add_u64 v[40:41], v[14:15], 0, s[10:11]
	global_load_dword v104, v[40:41], off
	v_lshl_add_u64 v[40:41], v[12:13], 0, s[10:11]
	global_load_dword v105, v[40:41], off
	v_lshl_add_u64 v[40:41], v[10:11], 0, s[10:11]
	global_load_dword v106, v[40:41], off
	v_lshl_add_u64 v[40:41], v[8:9], 0, s[10:11]
	global_load_dword v107, v[40:41], off
	s_add_u32 s10, s10, 0x42200
	s_addc_u32 s11, s11, 0
	v_lshl_add_u64 v[40:41], v[22:23], 0, s[10:11]
	global_load_dword v108, v[40:41], off
	v_lshl_add_u64 v[40:41], v[20:21], 0, s[10:11]
	global_load_dword v109, v[40:41], off
	v_lshl_add_u64 v[40:41], v[18:19], 0, s[10:11]
	global_load_dword v110, v[40:41], off
	v_lshl_add_u64 v[40:41], v[16:17], 0, s[10:11]
	global_load_dword v111, v[40:41], off
	v_lshl_add_u64 v[40:41], v[14:15], 0, s[10:11]
	global_load_dword v112, v[40:41], off
	v_lshl_add_u64 v[40:41], v[12:13], 0, s[10:11]
	global_load_dword v113, v[40:41], off
	v_lshl_add_u64 v[40:41], v[10:11], 0, s[10:11]
	global_load_dword v114, v[40:41], off
	v_lshl_add_u64 v[40:41], v[8:9], 0, s[10:11]
	global_load_dword v115, v[40:41], off
	s_add_u32 s10, s10, 0x42200
	s_addc_u32 s11, s11, 0
	v_lshl_add_u64 v[40:41], v[22:23], 0, s[10:11]
	global_load_dword v116, v[40:41], off
	v_lshl_add_u64 v[40:41], v[20:21], 0, s[10:11]
	global_load_dword v117, v[40:41], off
	v_lshl_add_u64 v[40:41], v[18:19], 0, s[10:11]
	global_load_dword v118, v[40:41], off
	v_lshl_add_u64 v[40:41], v[16:17], 0, s[10:11]
	global_load_dword v119, v[40:41], off
	v_lshl_add_u64 v[40:41], v[14:15], 0, s[10:11]
	global_load_dword v120, v[40:41], off
	v_lshl_add_u64 v[40:41], v[12:13], 0, s[10:11]
	global_load_dword v121, v[40:41], off
	v_lshl_add_u64 v[40:41], v[10:11], 0, s[10:11]
	global_load_dword v122, v[40:41], off
	v_lshl_add_u64 v[40:41], v[8:9], 0, s[10:11]
	global_load_dword v123, v[40:41], off
	s_add_u32 s10, s10, 0x42200
	s_addc_u32 s11, s11, 0
	v_lshl_add_u64 v[40:41], v[22:23], 0, s[10:11]
	global_load_dword v124, v[40:41], off
	v_lshl_add_u64 v[40:41], v[20:21], 0, s[10:11]
	global_load_dword v125, v[40:41], off
	v_lshl_add_u64 v[40:41], v[18:19], 0, s[10:11]
	global_load_dword v126, v[40:41], off
	v_lshl_add_u64 v[40:41], v[16:17], 0, s[10:11]
	global_load_dword v127, v[40:41], off
	v_lshl_add_u64 v[40:41], v[14:15], 0, s[10:11]
	global_load_dword v128, v[40:41], off
	v_lshl_add_u64 v[40:41], v[12:13], 0, s[10:11]
	global_load_dword v129, v[40:41], off
	v_lshl_add_u64 v[40:41], v[10:11], 0, s[10:11]
	global_load_dword v130, v[40:41], off
	v_lshl_add_u64 v[40:41], v[8:9], 0, s[10:11]
	global_load_dword v131, v[40:41], off
.Lp0win_skip:
	s_or_b64 exec, exec, s[12:13]
	s_waitcnt vmcnt(31)
	ds_write_b32 v3, v100
	s_waitcnt vmcnt(30)
	ds_write_b32 v3, v101 offset:264
	s_waitcnt vmcnt(29)
	ds_write_b32 v3, v102 offset:528
	s_waitcnt vmcnt(28)
	ds_write_b32 v3, v103 offset:792
	s_waitcnt vmcnt(27)
	ds_write_b32 v3, v104 offset:1056
	s_waitcnt vmcnt(26)
	ds_write_b32 v3, v105 offset:1320
	s_waitcnt vmcnt(25)
	ds_write_b32 v3, v106 offset:1584
	s_waitcnt vmcnt(24)
	ds_write_b32 v3, v107 offset:1848
	s_waitcnt vmcnt(23)
	ds_write_b32 v3, v108 offset:2112
	s_waitcnt vmcnt(22)
	ds_write_b32 v3, v109 offset:2376
	s_waitcnt vmcnt(21)
	ds_write_b32 v3, v110 offset:2640
	s_waitcnt vmcnt(20)
	ds_write_b32 v3, v111 offset:2904
	s_waitcnt vmcnt(19)
	ds_write_b32 v3, v112 offset:3168
	s_waitcnt vmcnt(18)
	ds_write_b32 v3, v113 offset:3432
	s_waitcnt vmcnt(17)
	ds_write_b32 v3, v114 offset:3696
	s_waitcnt vmcnt(16)
	ds_write_b32 v3, v115 offset:3960
	s_waitcnt vmcnt(15)
	ds_write_b32 v3, v116 offset:4224
	s_waitcnt vmcnt(14)
	ds_write_b32 v3, v117 offset:4488
	s_waitcnt vmcnt(13)
	ds_write_b32 v3, v118 offset:4752
	s_waitcnt vmcnt(12)
	ds_write_b32 v3, v119 offset:5016
	s_waitcnt vmcnt(11)
	ds_write_b32 v3, v120 offset:5280
	s_waitcnt vmcnt(10)
	ds_write_b32 v3, v121 offset:5544
	s_waitcnt vmcnt(9)
	ds_write_b32 v3, v122 offset:5808
	s_waitcnt vmcnt(8)
	ds_write_b32 v3, v123 offset:6072
	s_waitcnt vmcnt(7)
	ds_write_b32 v3, v124 offset:6336
	s_waitcnt vmcnt(6)
	ds_write_b32 v3, v125 offset:6600
	s_waitcnt vmcnt(5)
	ds_write_b32 v3, v126 offset:6864
	s_waitcnt vmcnt(4)
	ds_write_b32 v3, v127 offset:7128
	s_waitcnt vmcnt(3)
	ds_write_b32 v3, v128 offset:7392
	s_waitcnt vmcnt(2)
	ds_write_b32 v3, v129 offset:7656
	s_waitcnt vmcnt(1)
	ds_write_b32 v3, v130 offset:7920
	s_waitcnt vmcnt(0)
	ds_write_b32 v3, v131 offset:8184
	s_branch .LBB0_29

; __device__ __forceinline__ void fast_grid_barrier(unsigned* base, int seam, int tid) {
;     ...
;     if (tid == 0) {
;         unsigned* cnt = base + seam * 128;
;         unsigned* flg = cnt + 64;
;         __builtin_amdgcn_fence(__ATOMIC_RELEASE, "agent");
;         asm volatile("s_waitcnt vmcnt(0)" ::: "memory");
;         const unsigned old = __hip_atomic_fetch_add(cnt, 1u, __ATOMIC_RELAXED, __HIP_MEMORY_SCOPE_AGENT);
;         if (old == gridDim.x - 1) __hip_atomic_store(flg, 1u, __ATOMIC_RELAXED, __HIP_MEMORY_SCOPE_AGENT);
;         else { unsigned sp = 0; while (__hip_atomic_load(flg, __ATOMIC_RELAXED, __HIP_MEMORY_SCOPE_AGENT) == 0u) { __builtin_amdgcn_s_sleep(2); if (++sp > (1u << 22)) break; } }
;         __builtin_amdgcn_fence(__ATOMIC_ACQUIRE, "agent");
.LBB0_84:
	s_cmp_lt_i32 s47, 3
	s_cbranch_scc1 .LBB0_101
	s_waitcnt vmcnt(0)
	v_cmp_eq_u32_e32 vcc, 0, v202
	s_barrier
	s_and_saveexec_b64 s[0:1], vcc
	s_cbranch_execz .LBB0_100
	s_load_dwordx2 s[4:5], s[84:85], 0x90
	s_lshl_b32 s3, s98, 6
	v_mov_b32_e32 v0, s3
	v_mov_b32_e32 v2, 1
	s_waitcnt lgkmcnt(0)
	s_add_u32 s4, s4, 0x1400
	s_addc_u32 s5, s5, 0
	s_lshl_b32 s6, s98, 2
	v_mov_b32_e32 v1, s6
	v_mov_b32_e32 v2, 0
	global_load_dword v1, v1, s[4:5] sc1
	global_load_dword v2, v2, s[4:5] offset:64 sc1
	s_waitcnt vmcnt(0)
	v_readfirstlane_b32 s99, v1
	v_readfirstlane_b32 s100, v2
	v_mov_b32_e32 v2, 1
	s_nop 3
	global_atomic_add v1, v0, v2, s[4:5] offset:128 sc0
	s_mul_i32 s6, s99, 1
	s_add_i32 s3, s6, -1
	s_lshl_b32 s6, s98, 6
	s_sub_u32 s6, s4, s6
	s_subb_u32 s7, s5, 0
	s_waitcnt vmcnt(0)
	v_cmp_ne_u32_e32 vcc, s3, v1
	s_cbranch_vccnz .Lsm1_wtop
	buffer_wbl2 sc1
	s_waitcnt vmcnt(0)
	global_atomic_add v1, v0, v2, s[6:7] offset:2176 sc0
	s_mul_i32 s3, s100, 1
	s_add_i32 s3, s3, -1
	s_waitcnt vmcnt(0)
	v_cmp_ne_u32_e32 vcc, s3, v1
	v_mov_b32_e32 v1, 1
	s_cbranch_vccnz .Lsm1_wtop
	global_store_dword v0, v1, s[6:7] offset:2304 sc1
	s_branch .Lsm1_topdone

; __device__ __forceinline__ void fast_grid_barrier(unsigned* base, int seam, int tid) {
;     ...
;         asm volatile("s_waitcnt vmcnt(0)" ::: "memory");
;         const unsigned old = __hip_atomic_fetch_add(cnt, 1u, __ATOMIC_RELAXED, __HIP_MEMORY_SCOPE_AGENT);
;         if (old == gridDim.x - 1) __hip_atomic_store(flg, 1u, __ATOMIC_RELAXED, __HIP_MEMORY_SCOPE_AGENT);
;         else { unsigned sp = 0; while (__hip_atomic_load(flg, __ATOMIC_RELAXED, __HIP_MEMORY_SCOPE_AGENT) == 0u) { __builtin_amdgcn_s_sleep(2); if (++sp > (1u << 22)) break; } }
;         __builtin_amdgcn_fence(__ATOMIC_ACQUIRE, "agent");
;         asm volatile("s_waitcnt vmcnt(0)" ::: "memory");
.Lsm1_topdone:
	s_waitcnt vmcnt(0)
	buffer_inv sc1
	s_waitcnt vmcnt(0)

; __device__ __forceinline__ void fast_grid_barrier(unsigned* base, int seam, int tid) {
;     ...
;     if (tid == 0) {
;         unsigned* cnt = base + seam * 128;
;         unsigned* flg = cnt + 64;
;         __builtin_amdgcn_fence(__ATOMIC_RELEASE, "agent");
;         asm volatile("s_waitcnt vmcnt(0)" ::: "memory");
;         const unsigned old = __hip_atomic_fetch_add(cnt, 1u, __ATOMIC_RELAXED, __HIP_MEMORY_SCOPE_AGENT);
;         if (old == gridDim.x - 1) __hip_atomic_store(flg, 1u, __ATOMIC_RELAXED, __HIP_MEMORY_SCOPE_AGENT);
;         else { unsigned sp = 0; while (__hip_atomic_load(flg, __ATOMIC_RELAXED, __HIP_MEMORY_SCOPE_AGENT) == 0u) { __builtin_amdgcn_s_sleep(2); if (++sp > (1u << 22)) break; } }
;         __builtin_amdgcn_fence(__ATOMIC_ACQUIRE, "agent");
.LBB0_167:
	s_waitcnt vmcnt(0)
	v_cmp_eq_u32_e32 vcc, 0, v202
	s_waitcnt vmcnt(0) lgkmcnt(0)
	s_barrier
	s_and_saveexec_b64 s[0:1], vcc
	s_cbranch_execz .LBB0_182
	s_load_dwordx2 s[4:5], s[84:85], 0x90
	s_lshl_b32 s3, s98, 6
	v_mov_b32_e32 v0, s3
	v_mov_b32_e32 v2, 1
	s_waitcnt lgkmcnt(0)
	s_add_u32 s4, s4, 0x1400
	s_addc_u32 s5, s5, 0
	global_atomic_add v1, v0, v2, s[4:5] offset:128 sc0
	s_mul_i32 s6, s99, 2
	s_add_i32 s3, s6, -1
	s_lshl_b32 s6, s98, 6
	s_sub_u32 s6, s4, s6
	s_subb_u32 s7, s5, 0
	s_waitcnt vmcnt(0)
	v_cmp_ne_u32_e32 vcc, s3, v1
	s_cbranch_vccnz .Lsm2_wtop
	buffer_wbl2 sc1
	s_waitcnt vmcnt(0)
	global_atomic_add v1, v0, v2, s[6:7] offset:2176 sc0
	s_mul_i32 s3, s100, 2
	s_add_i32 s3, s3, -1
	s_waitcnt vmcnt(0)
	v_cmp_ne_u32_e32 vcc, s3, v1
	v_mov_b32_e32 v1, 2
	s_cbranch_vccnz .Lsm2_wtop
	global_store_dword v0, v1, s[6:7] offset:2304 sc1
	s_branch .Lsm2_topdone

; __device__ __forceinline__ void fast_grid_barrier(unsigned* base, int seam, int tid) {
;     ...
;     if (tid == 0) {
;         unsigned* cnt = base + seam * 128;
;         unsigned* flg = cnt + 64;
;         __builtin_amdgcn_fence(__ATOMIC_RELEASE, "agent");
;         asm volatile("s_waitcnt vmcnt(0)" ::: "memory");
;         const unsigned old = __hip_atomic_fetch_add(cnt, 1u, __ATOMIC_RELAXED, __HIP_MEMORY_SCOPE_AGENT);
;         if (old == gridDim.x - 1) __hip_atomic_store(flg, 1u, __ATOMIC_RELAXED, __HIP_MEMORY_SCOPE_AGENT);
;         else { unsigned sp = 0; while (__hip_atomic_load(flg, __ATOMIC_RELAXED, __HIP_MEMORY_SCOPE_AGENT) == 0u) { __builtin_amdgcn_s_sleep(2); if (++sp > (1u << 22)) break; } }
;         __builtin_amdgcn_fence(__ATOMIC_ACQUIRE, "agent");
.LBB0_544:
	s_waitcnt lgkmcnt(0)
	s_cmp_lt_i32 s47, 5
	s_cbranch_scc1 .LBB0_561
	s_waitcnt vmcnt(0)
	s_waitcnt vmcnt(0)
	s_barrier
	s_mov_b64 s[0:1], exec
	v_readlane_b32 s4, v249, 28
	v_readlane_b32 s5, v249, 29
	s_and_b64 s[4:5], s[0:1], s[4:5]
	s_mov_b64 exec, s[4:5]
	s_cbranch_execz .LBB0_560
	s_load_dwordx2 s[4:5], s[84:85], 0x90
	s_lshl_b32 s3, s98, 6
	v_mov_b32_e32 v0, s3
	v_mov_b32_e32 v2, 1
	s_waitcnt lgkmcnt(0)
	s_add_u32 s4, s4, 0x1400
	s_addc_u32 s5, s5, 0
	global_atomic_add v1, v0, v2, s[4:5] offset:128 sc0
	s_mul_i32 s6, s99, 3
	s_add_i32 s3, s6, -1
	s_lshl_b32 s6, s98, 6
	s_sub_u32 s6, s4, s6
	s_subb_u32 s7, s5, 0
	s_waitcnt vmcnt(0)
	v_cmp_ne_u32_e32 vcc, s3, v1
	s_cbranch_vccnz .Lsm3_wtop
	buffer_wbl2 sc1
	s_waitcnt vmcnt(0)
	global_atomic_add v1, v0, v2, s[6:7] offset:2176 sc0
	s_mul_i32 s3, s100, 3
	s_add_i32 s3, s3, -1
	s_waitcnt vmcnt(0)
	v_cmp_ne_u32_e32 vcc, s3, v1
	v_mov_b32_e32 v1, 3
	s_cbranch_vccnz .Lsm3_wtop
	global_store_dword v0, v1, s[6:7] offset:2304 sc1
	s_branch .Lsm3_topdone

; __device__ __forceinline__ void fast_grid_barrier(unsigned* base, int seam, int tid) {
;     ...
;     if (tid == 0) {
;         unsigned* cnt = base + seam * 128;
;         unsigned* flg = cnt + 64;
;         __builtin_amdgcn_fence(__ATOMIC_RELEASE, "agent");
;         asm volatile("s_waitcnt vmcnt(0)" ::: "memory");
;         const unsigned old = __hip_atomic_fetch_add(cnt, 1u, __ATOMIC_RELAXED, __HIP_MEMORY_SCOPE_AGENT);
;         if (old == gridDim.x - 1) __hip_atomic_store(flg, 1u, __ATOMIC_RELAXED, __HIP_MEMORY_SCOPE_AGENT);
;         else { unsigned sp = 0; while (__hip_atomic_load(flg, __ATOMIC_RELAXED, __HIP_MEMORY_SCOPE_AGENT) == 0u) { __builtin_amdgcn_s_sleep(2); if (++sp > (1u << 22)) break; } }
;         __builtin_amdgcn_fence(__ATOMIC_ACQUIRE, "agent");
.LBB0_586:
	s_waitcnt lgkmcnt(0)
	s_cmp_lt_i32 s47, 6
	s_cbranch_scc1 .LBB0_603
	s_waitcnt vmcnt(0)
	v_cmp_eq_u32_e32 vcc, 0, v202
	s_barrier
	s_and_saveexec_b64 s[0:1], vcc
	s_cbranch_execz .LBB0_602
	s_load_dwordx2 s[4:5], s[84:85], 0x90
	s_lshl_b32 s3, s98, 6
	v_mov_b32_e32 v0, s3
	v_mov_b32_e32 v2, 1
	s_waitcnt lgkmcnt(0)
	s_add_u32 s4, s4, 0x1400
	s_addc_u32 s5, s5, 0
	global_atomic_add v1, v0, v2, s[4:5] offset:128 sc0
	s_mul_i32 s6, s99, 4
	s_add_i32 s3, s6, -1
	s_lshl_b32 s6, s98, 6
	s_sub_u32 s6, s4, s6
	s_subb_u32 s7, s5, 0
	s_waitcnt vmcnt(0)
	v_cmp_ne_u32_e32 vcc, s3, v1
	s_cbranch_vccnz .Lsm4_wtop
	buffer_wbl2 sc1
	s_waitcnt vmcnt(0)
	global_atomic_add v1, v0, v2, s[6:7] offset:2176 sc0
	s_mul_i32 s3, s100, 4
	s_add_i32 s3, s3, -1
	s_waitcnt vmcnt(0)
	v_cmp_ne_u32_e32 vcc, s3, v1
	v_mov_b32_e32 v1, 4
	s_cbranch_vccnz .Lsm4_wtop
	global_store_dword v0, v1, s[6:7] offset:2304 sc1
	s_branch .Lsm4_topdone

; __device__ __forceinline__ void fast_grid_barrier(unsigned* base, int seam, int tid) {
;     ...
;     if (tid == 0) {
;         unsigned* cnt = base + seam * 128;
;         unsigned* flg = cnt + 64;
;         __builtin_amdgcn_fence(__ATOMIC_RELEASE, "agent");
;         asm volatile("s_waitcnt vmcnt(0)" ::: "memory");
;         const unsigned old = __hip_atomic_fetch_add(cnt, 1u, __ATOMIC_RELAXED, __HIP_MEMORY_SCOPE_AGENT);
;         if (old == gridDim.x - 1) __hip_atomic_store(flg, 1u, __ATOMIC_RELAXED, __HIP_MEMORY_SCOPE_AGENT);
;         else { unsigned sp = 0; while (__hip_atomic_load(flg, __ATOMIC_RELAXED, __HIP_MEMORY_SCOPE_AGENT) == 0u) { __builtin_amdgcn_s_sleep(2); if (++sp > (1u << 22)) break; } }
;         __builtin_amdgcn_fence(__ATOMIC_ACQUIRE, "agent");
.LBB0_609:
	s_cmp_lt_i32 s47, 7
	s_cbranch_scc1 .LBB0_626
	s_waitcnt vmcnt(0)
	v_cmp_eq_u32_e32 vcc, 0, v202
	s_waitcnt vmcnt(0) lgkmcnt(0)
	s_barrier
	s_and_saveexec_b64 s[0:1], vcc
	s_cbranch_execz .LBB0_625
	s_load_dwordx2 s[4:5], s[84:85], 0x90
	s_lshl_b32 s3, s98, 6
	v_mov_b32_e32 v0, s3
	v_mov_b32_e32 v2, 1
	s_waitcnt lgkmcnt(0)
	s_add_u32 s4, s4, 0x1400
	s_addc_u32 s5, s5, 0
	global_atomic_add v1, v0, v2, s[4:5] offset:128 sc0
	s_mul_i32 s6, s99, 5
	s_add_i32 s3, s6, -1
	s_lshl_b32 s6, s98, 6
	s_sub_u32 s6, s4, s6
	s_subb_u32 s7, s5, 0
	s_waitcnt vmcnt(0)
	v_cmp_ne_u32_e32 vcc, s3, v1
	s_cbranch_vccnz .Lsm5_wtop
	buffer_wbl2 sc1
	s_waitcnt vmcnt(0)
	global_atomic_add v1, v0, v2, s[6:7] offset:2176 sc0
	s_mul_i32 s3, s100, 5
	s_add_i32 s3, s3, -1
	s_waitcnt vmcnt(0)
	v_cmp_ne_u32_e32 vcc, s3, v1
	v_mov_b32_e32 v1, 5
	s_cbranch_vccnz .Lsm5_wtop
	global_store_dword v0, v1, s[6:7] offset:2304 sc1
	s_branch .Lsm5_topdone

; __device__ __forceinline__ void fast_grid_barrier(unsigned* base, int seam, int tid) {
;     ...
;     if (tid == 0) {
;         unsigned* cnt = base + seam * 128;
;         unsigned* flg = cnt + 64;
;         __builtin_amdgcn_fence(__ATOMIC_RELEASE, "agent");
;         asm volatile("s_waitcnt vmcnt(0)" ::: "memory");
;         const unsigned old = __hip_atomic_fetch_add(cnt, 1u, __ATOMIC_RELAXED, __HIP_MEMORY_SCOPE_AGENT);
;         if (old == gridDim.x - 1) __hip_atomic_store(flg, 1u, __ATOMIC_RELAXED, __HIP_MEMORY_SCOPE_AGENT);
;         else { unsigned sp = 0; while (__hip_atomic_load(flg, __ATOMIC_RELAXED, __HIP_MEMORY_SCOPE_AGENT) == 0u) { __builtin_amdgcn_s_sleep(2); if (++sp > (1u << 22)) break; } }
;         __builtin_amdgcn_fence(__ATOMIC_ACQUIRE, "agent");
.LBB0_692:
	s_waitcnt vmcnt(0)
	v_cmp_eq_u32_e32 vcc, 0, v202
	s_waitcnt vmcnt(0) lgkmcnt(0)
	s_barrier
	s_and_saveexec_b64 s[0:1], vcc
	s_cbranch_execz .LBB0_707
	s_load_dwordx2 s[4:5], s[84:85], 0x90
	s_lshl_b32 s3, s98, 6
	v_mov_b32_e32 v0, s3
	v_mov_b32_e32 v2, 1
	s_waitcnt lgkmcnt(0)
	s_add_u32 s4, s4, 0x1400
	s_addc_u32 s5, s5, 0
	global_atomic_add v1, v0, v2, s[4:5] offset:128 sc0
	s_mul_i32 s6, s99, 6
	s_add_i32 s3, s6, -1
	s_lshl_b32 s6, s98, 6
	s_sub_u32 s6, s4, s6
	s_subb_u32 s7, s5, 0
	s_waitcnt vmcnt(0)
	v_cmp_ne_u32_e32 vcc, s3, v1
	s_cbranch_vccnz .Lsm6_wtop
	buffer_wbl2 sc1
	s_waitcnt vmcnt(0)
	global_atomic_add v1, v0, v2, s[6:7] offset:2176 sc0
	s_mul_i32 s3, s100, 6
	s_add_i32 s3, s3, -1
	s_waitcnt vmcnt(0)
	v_cmp_ne_u32_e32 vcc, s3, v1
	v_mov_b32_e32 v1, 6
	s_cbranch_vccnz .Lsm6_wtop
	global_store_dword v0, v1, s[6:7] offset:2304 sc1
	s_branch .Lsm6_topdone

; __device__ __forceinline__ void fast_grid_barrier(unsigned* base, int seam, int tid) {
;     ...
;     if (tid == 0) {
;         unsigned* cnt = base + seam * 128;
;         unsigned* flg = cnt + 64;
;         __builtin_amdgcn_fence(__ATOMIC_RELEASE, "agent");
;         asm volatile("s_waitcnt vmcnt(0)" ::: "memory");
;         const unsigned old = __hip_atomic_fetch_add(cnt, 1u, __ATOMIC_RELAXED, __HIP_MEMORY_SCOPE_AGENT);
;         if (old == gridDim.x - 1) __hip_atomic_store(flg, 1u, __ATOMIC_RELAXED, __HIP_MEMORY_SCOPE_AGENT);
;         else { unsigned sp = 0; while (__hip_atomic_load(flg, __ATOMIC_RELAXED, __HIP_MEMORY_SCOPE_AGENT) == 0u) { __builtin_amdgcn_s_sleep(2); if (++sp > (1u << 22)) break; } }
;         __builtin_amdgcn_fence(__ATOMIC_ACQUIRE, "agent");
.LBB0_1069:
	s_waitcnt lgkmcnt(0)
	s_cmp_lt_i32 s47, 9
	s_cbranch_scc1 .LBB0_1086
	s_waitcnt vmcnt(0)
	s_barrier
	s_mov_b64 s[0:1], exec
	v_readlane_b32 s4, v249, 8
	v_readlane_b32 s5, v249, 9
	s_and_b64 s[4:5], s[0:1], s[4:5]
	s_mov_b64 exec, s[4:5]
	s_cbranch_execz .LBB0_1085
	s_load_dwordx2 s[4:5], s[84:85], 0x90
	s_lshl_b32 s3, s98, 6
	v_mov_b32_e32 v0, s3
	v_mov_b32_e32 v2, 1
	s_waitcnt lgkmcnt(0)
	s_add_u32 s4, s4, 0x1400
	s_addc_u32 s5, s5, 0
	global_atomic_add v1, v0, v2, s[4:5] offset:128 sc0
	s_mul_i32 s6, s99, 7
	s_add_i32 s3, s6, -1
	s_lshl_b32 s6, s98, 6
	s_sub_u32 s6, s4, s6
	s_subb_u32 s7, s5, 0
	s_waitcnt vmcnt(0)
	v_cmp_ne_u32_e32 vcc, s3, v1
	s_cbranch_vccnz .Lsm7_wtop
	buffer_wbl2 sc1
	s_waitcnt vmcnt(0)
	global_atomic_add v1, v0, v2, s[6:7] offset:2176 sc0
	s_mul_i32 s3, s100, 7
	s_add_i32 s3, s3, -1
	s_waitcnt vmcnt(0)
	v_cmp_ne_u32_e32 vcc, s3, v1
	v_mov_b32_e32 v1, 7
	s_cbranch_vccnz .Lsm7_wtop
	global_store_dword v0, v1, s[6:7] offset:2304 sc1
	s_branch .Lsm7_topdone
